# v126 + row statistics of each StaticOrder unit staged into spare LDS by two LDS-DMAs at unit start, epilogue head reads them with ds_read (no global loads / vmcnt(0) at the head)
# baseline (speedup 1.0000x reference)
; #define PG8_STAGE(bufoff, gbase, voff) do { _Pragma("unroll") for (int _i = 0; _i < 2; ++_i) \
;         __builtin_amdgcn_global_load_lds((const unsigned*)((const char*)(gbase) + (voff)[_i]), (PG8_LAS unsigned*)(lds + (bufoff) + ldsw + _i * 8192), 16, 0, 0); } while (0)
; #define PG8_LDA(dst, b, h) do { _Pragma("unroll") for (int m = 0; m < 4; ++m) _Pragma("unroll") for (int k = 0; k < 2; ++k) dst[m][k] = *(const PG8_LAS bf16x8*)(lds + PG8_SA(b, h) + aoff + m * 2048 + k * 1024); } while (0)
; #define PG8_LDB(dst, b, h) do { _Pragma("unroll") for (int n = 0; n < 2; ++n) _Pragma("unroll") for (int k = 0; k < 2; ++k) dst[n][k] = *(const PG8_LAS bf16x8*)(lds + PG8_SB(b, h) + boff + n * 2048 + k * 1024); } while (0)
; #define PG8_MMA(ai, bj, At, Bt) do { __builtin_amdgcn_s_setprio(1); _Pragma("unroll") for (int m = 0; m < 4; ++m) _Pragma("unroll") for (int n = 0; n < 2; ++n) _Pragma("unroll") for (int k = 0; k < 2; ++k) \
;         acc[ai][bj][m][n] = __builtin_amdgcn_mfma_f32_16x16x32_bf16(Bt[n][k], At[m][k], acc[ai][bj][m][n], 0, 0, 0); __builtin_amdgcn_s_setprio(0); } while (0)
; #define PG8_WAIT_V(n) asm volatile("s_waitcnt vmcnt(" #n ")" ::: "memory")
; #define PG8_WAIT_L(n) asm volatile("s_waitcnt lgkmcnt(" #n ")" ::: "memory")
; #define PG8_BAR __builtin_amdgcn_s_barrier()
; #define PG8_SCHED __builtin_amdgcn_sched_barrier(0)
;     __device__ __forceinline__ void operator()(const f32x4 (&acc)[2][2][4][2], const Unit& u, int wr, int wc, int fr, int fq) const {
;     ...
;             for (int m = 0; m < 4; ++m) rs[ai][m] = ss[row0 + ai * HALF + m * 16];
; template <class Epi, class Sched, bool ALIGN_EPI = false, bool SP2 = false>
; __device__ __forceinline__ void gemm_phase(PG8_LAS unsigned char* lds, const Gemm g, const Sched& S, const Epi& E) {
;     ...
;             if (last && has_next) S.a_ready(nxt);
;             if constexpr (SP2) {
;             PG8_LDB(B0, 0, 0); PG8_LDB(B1, 0, 1); PG8_SCHED; PG8_LDA(At, 0, 0); PG8_STAGE(PG8_SA(1, 1), a1 + hstepA, voffA);
;             PG8_WAIT_V(8); PG8_WAIT_L(0); PG8_BAR; PG8_MMA(0, 0, At, B0); PG8_MMA(0, 1, At, B1); PG8_BAR; PG8_SCHED;
;             PG8_LDA(At, 0, 1); PG8_STAGE(PG8_SB(0, 0), b2, voffB); PG8_STAGE(PG8_SB(0, 1), b2 + hstepB, voffB); PG8_STAGE(PG8_SA(0, 0), a2, voffA);
.LBB0_276:
	s_ashr_i32 s29, s28, 31
	s_lshl_b64 s[34:35], s[28:29], 20
	s_add_u32 s34, s96, s34
	s_addc_u32 s35, s97, s35
	s_and_b64 s[36:37], s[30:31], exec
	s_cselect_b32 s29, s35, s43
	s_cselect_b32 s52, s34, s42
	s_ashr_i32 s27, s26, 31
	s_lshl_b64 s[36:37], s[26:27], 20
	s_add_u32 s36, s8, s36
	s_addc_u32 s37, s9, s37
	s_and_b64 s[44:45], s[30:31], exec
	s_cselect_b32 s27, s37, s41
	s_cselect_b32 s53, s36, s40
	s_add_u32 s54, s40, 0x10000
	s_addc_u32 s55, s41, 0
	s_add_u32 s40, s42, 0x80080
	s_addc_u32 s41, s43, 0
	s_mov_b32 s56, -2
	v_lshlrev_b32_e32 v136, 2, v202
	s_lshl_b32 s100, s38, 10
	s_lshr_b32 s98, s10, 12
	s_lshl_b32 s98, s98, 8
	s_add_u32 s100, s100, s98
	s_add_u32 s100, s18, s100
	s_addc_u32 s101, s19, 0
	s_lshr_b32 s98, s10, 1
	s_add_i32 s98, s98, 0x20000
	s_mov_b32 m0, s98
	s_nop 0
	global_load_lds_dword v136, s[100:101]
	s_add_u32 s100, s100, 0x200
	s_addc_u32 s101, s101, 0
	s_add_i32 m0, s98, 0x100
	s_nop 0
	global_load_lds_dword v136, s[100:101]
	s_sub_u32 s100, s40, 0x80000
	s_subb_u32 s101, s41, 0
	ds_read_b128 v[136:139], v129
	ds_read_b128 v[146:149], v129 offset:1024
	ds_read_b128 v[150:153], v129 offset:2048
	ds_read_b128 v[154:157], v129 offset:3072
	ds_read_b128 v[158:161], v143
	ds_read_b128 v[162:165], v143 offset:1024
	ds_read_b128 v[166:169], v143 offset:2048
	ds_read_b128 v[170:173], v143 offset:3072
	s_add_u32 s42, s40, 0xfff80080
	s_addc_u32 s43, s41, -1
	s_cmp_eq_u32 s56, 28
	s_cselect_b32 s45, s29, s43
	s_cselect_b32 s44, s52, s42
	s_cselect_b32 s43, s27, s55
	s_cselect_b32 s42, s53, s54
	ds_read_b128 v[174:177], v144
	ds_read_b128 v[178:181], v144 offset:1024
	ds_read_b128 v[182:185], v144 offset:2048
	ds_read_b128 v[204:207], v144 offset:3072
	ds_read_b128 v[208:211], v144 offset:4096
	ds_read_b128 v[212:215], v144 offset:5120
	ds_read_b128 v[216:219], v144 offset:6144
	ds_read_b128 v[220:223], v144 offset:7168
	s_mov_b32 m0, s15
	s_nop 0
	global_load_lds_dwordx4 v132, s[100:101]
	s_mov_b32 m0, s47
	s_nop 0
	global_load_lds_dwordx4 v134, s[100:101]
	s_add_i32 m0, s10, 0xc000
	s_nop 0
	global_load_lds_dwordx4 v132, s[40:41]
	s_add_i32 m0, s10, 0xe000
	s_nop 0
	global_load_lds_dwordx4 v134, s[40:41]
	s_waitcnt vmcnt(8)
	s_waitcnt lgkmcnt(0)
	s_setprio 1
	s_barrier
	v_mfma_f32_16x16x32_bf16 v[124:127], v[136:139], v[174:177], 0
	v_mfma_f32_16x16x32_bf16 v[120:123], v[150:153], v[174:177], 0
	v_mfma_f32_16x16x32_bf16 v[108:111], v[136:139], v[182:185], 0
	v_mfma_f32_16x16x32_bf16 v[104:107], v[150:153], v[182:185], 0
	v_mfma_f32_16x16x32_bf16 v[92:95], v[136:139], v[208:211], 0
	v_mfma_f32_16x16x32_bf16 v[88:91], v[150:153], v[208:211], 0
	v_mfma_f32_16x16x32_bf16 v[76:79], v[136:139], v[216:219], 0
	v_mfma_f32_16x16x32_bf16 v[72:75], v[150:153], v[216:219], 0
	v_mfma_f32_16x16x32_bf16 v[124:127], v[146:149], v[178:181], v[124:127]
	v_mfma_f32_16x16x32_bf16 v[120:123], v[154:157], v[178:181], v[120:123]
	v_mfma_f32_16x16x32_bf16 v[108:111], v[146:149], v[204:207], v[108:111]
	v_mfma_f32_16x16x32_bf16 v[104:107], v[154:157], v[204:207], v[104:107]
	v_mfma_f32_16x16x32_bf16 v[92:95], v[146:149], v[212:215], v[92:95]
	v_mfma_f32_16x16x32_bf16 v[88:91], v[154:157], v[212:215], v[88:91]
	v_mfma_f32_16x16x32_bf16 v[76:79], v[146:149], v[220:223], v[76:79]
	v_mfma_f32_16x16x32_bf16 v[72:75], v[154:157], v[220:223], v[72:75]
	v_mfma_f32_16x16x32_bf16 v[116:119], v[158:161], v[174:177], 0
	v_mfma_f32_16x16x32_bf16 v[112:115], v[166:169], v[174:177], 0
	v_mfma_f32_16x16x32_bf16 v[100:103], v[158:161], v[182:185], 0
	v_mfma_f32_16x16x32_bf16 v[96:99], v[166:169], v[182:185], 0
	v_mfma_f32_16x16x32_bf16 v[84:87], v[158:161], v[208:211], 0
	v_mfma_f32_16x16x32_bf16 v[80:83], v[166:169], v[208:211], 0
	v_mfma_f32_16x16x32_bf16 v[68:71], v[158:161], v[216:219], 0
	v_mfma_f32_16x16x32_bf16 v[64:67], v[166:169], v[216:219], 0
	v_mfma_f32_16x16x32_bf16 v[116:119], v[162:165], v[178:181], v[116:119]
	v_mfma_f32_16x16x32_bf16 v[112:115], v[170:173], v[178:181], v[112:115]
	v_mfma_f32_16x16x32_bf16 v[100:103], v[162:165], v[204:207], v[100:103]
	v_mfma_f32_16x16x32_bf16 v[96:99], v[170:173], v[204:207], v[96:99]
	v_mfma_f32_16x16x32_bf16 v[84:87], v[162:165], v[212:215], v[84:87]
	v_mfma_f32_16x16x32_bf16 v[80:83], v[170:173], v[212:215], v[80:83]
	v_mfma_f32_16x16x32_bf16 v[68:71], v[162:165], v[220:223], v[68:71]
	v_mfma_f32_16x16x32_bf16 v[64:67], v[170:173], v[220:223], v[64:67]
	s_barrier
	s_add_u32 s98, s44, s20
	s_addc_u32 s99, s45, s21
	s_setprio 0
	s_add_i32 s57, s49, s2
	s_mov_b32 m0, s57
	ds_read_b128 v[174:177], v144 offset:16384
	ds_read_b128 v[178:181], v144 offset:17408
	ds_read_b128 v[182:185], v144 offset:18432
	ds_read_b128 v[204:207], v144 offset:19456
	ds_read_b128 v[208:211], v144 offset:20480
	ds_read_b128 v[212:215], v144 offset:21504
	ds_read_b128 v[216:219], v144 offset:22528
	ds_read_b128 v[220:223], v144 offset:23552
	global_load_lds_dwordx4 v194, s[42:43]
	s_add_i32 m0, s57, 0x2000
	s_add_u32 s58, s42, 0x4000
	s_addc_u32 s59, s43, 0
	s_add_i32 s57, s50, s2
	global_load_lds_dwordx4 v198, s[42:43]
	s_mov_b32 m0, s57
	s_nop 0
	global_load_lds_dwordx4 v194, s[58:59]
	s_add_i32 m0, s57, 0x2000
	s_nop 0
	global_load_lds_dwordx4 v198, s[58:59]
	s_waitcnt vmcnt(6)
	s_waitcnt lgkmcnt(0)
	s_setprio 1
	s_barrier
; #define PG8_STAGE(bufoff, gbase, voff) do { _Pragma("unroll") for (int _i = 0; _i < 2; ++_i) \
;         __builtin_amdgcn_global_load_lds((const unsigned*)((const char*)(gbase) + (voff)[_i]), (PG8_LAS unsigned*)(lds + (bufoff) + ldsw + _i * 8192), 16, 0, 0); } while (0)
; #define PG8_LDA(dst, b, h) do { _Pragma("unroll") for (int m = 0; m < 4; ++m) _Pragma("unroll") for (int k = 0; k < 2; ++k) dst[m][k] = *(const PG8_LAS bf16x8*)(lds + PG8_SA(b, h) + aoff + m * 2048 + k * 1024); } while (0)
; #define PG8_LDB(dst, b, h) do { _Pragma("unroll") for (int n = 0; n < 2; ++n) _Pragma("unroll") for (int k = 0; k < 2; ++k) dst[n][k] = *(const PG8_LAS bf16x8*)(lds + PG8_SB(b, h) + boff + n * 2048 + k * 1024); } while (0)
; #define PG8_MMA(ai, bj, At, Bt) do { __builtin_amdgcn_s_setprio(1); _Pragma("unroll") for (int m = 0; m < 4; ++m) _Pragma("unroll") for (int n = 0; n < 2; ++n) _Pragma("unroll") for (int k = 0; k < 2; ++k) \
;         acc[ai][bj][m][n] = __builtin_amdgcn_mfma_f32_16x16x32_bf16(Bt[n][k], At[m][k], acc[ai][bj][m][n], 0, 0, 0); __builtin_amdgcn_s_setprio(0); } while (0)
; #define PG8_WAIT_V(n) asm volatile("s_waitcnt vmcnt(" #n ")" ::: "memory")
; #define PG8_WAIT_L(n) asm volatile("s_waitcnt lgkmcnt(" #n ")" ::: "memory")
; #define PG8_BAR __builtin_amdgcn_s_barrier()
; #define PG8_SCHED __builtin_amdgcn_sched_barrier(0)
; template <class Epi, class Sched, bool ALIGN_EPI = false, bool SP2 = false>
; __device__ __forceinline__ void gemm_phase(PG8_LAS unsigned char* lds, const Gemm g, const Sched& S, const Epi& E) {
;     ...
;             PG8_WAIT_V(8); PG8_WAIT_L(0); PG8_BAR; PG8_MMA(1, 0, At, B0); PG8_MMA(1, 1, At, B1); PG8_BAR; PG8_SCHED;
;             PG8_LDB(B0, 1, 0); PG8_LDB(B1, 1, 1); PG8_SCHED; PG8_LDA(At, 1, 0); PG8_STAGE(PG8_SA(0, 1), a2 + hstepA, voffA);
;             PG8_WAIT_V(8); PG8_WAIT_L(0); PG8_BAR; PG8_MMA(0, 0, At, B0); PG8_MMA(0, 1, At, B1); PG8_BAR; PG8_SCHED;
	v_mfma_f32_16x16x32_bf16 v[60:63], v[136:139], v[174:177], 0
	v_mfma_f32_16x16x32_bf16 v[56:59], v[150:153], v[174:177], 0
	v_mfma_f32_16x16x32_bf16 v[44:47], v[136:139], v[182:185], 0
	v_mfma_f32_16x16x32_bf16 v[40:43], v[150:153], v[182:185], 0
	v_mfma_f32_16x16x32_bf16 v[28:31], v[136:139], v[208:211], 0
	v_mfma_f32_16x16x32_bf16 v[24:27], v[150:153], v[208:211], 0
	v_mfma_f32_16x16x32_bf16 v[12:15], v[136:139], v[216:219], 0
	v_mfma_f32_16x16x32_bf16 v[8:11], v[150:153], v[216:219], 0
	v_mfma_f32_16x16x32_bf16 v[60:63], v[146:149], v[178:181], v[60:63]
	v_mfma_f32_16x16x32_bf16 v[56:59], v[154:157], v[178:181], v[56:59]
	v_mfma_f32_16x16x32_bf16 v[44:47], v[146:149], v[204:207], v[44:47]
	v_mfma_f32_16x16x32_bf16 v[40:43], v[154:157], v[204:207], v[40:43]
	v_mfma_f32_16x16x32_bf16 v[28:31], v[146:149], v[212:215], v[28:31]
	v_mfma_f32_16x16x32_bf16 v[24:27], v[154:157], v[212:215], v[24:27]
	v_mfma_f32_16x16x32_bf16 v[12:15], v[146:149], v[220:223], v[12:15]
	v_mfma_f32_16x16x32_bf16 v[8:11], v[154:157], v[220:223], v[8:11]
	v_mfma_f32_16x16x32_bf16 v[52:55], v[158:161], v[174:177], 0
	v_mfma_f32_16x16x32_bf16 v[48:51], v[166:169], v[174:177], 0
	v_mfma_f32_16x16x32_bf16 v[36:39], v[158:161], v[182:185], 0
	v_mfma_f32_16x16x32_bf16 v[32:35], v[166:169], v[182:185], 0
	v_mfma_f32_16x16x32_bf16 v[20:23], v[158:161], v[208:211], 0
	v_mfma_f32_16x16x32_bf16 v[16:19], v[166:169], v[208:211], 0
	v_mfma_f32_16x16x32_bf16 v[4:7], v[158:161], v[216:219], 0
	v_mfma_f32_16x16x32_bf16 v[0:3], v[166:169], v[216:219], 0
	v_mfma_f32_16x16x32_bf16 v[52:55], v[162:165], v[178:181], v[52:55]
	v_mfma_f32_16x16x32_bf16 v[48:51], v[170:173], v[178:181], v[48:51]
	v_mfma_f32_16x16x32_bf16 v[36:39], v[162:165], v[204:207], v[36:39]
	v_mfma_f32_16x16x32_bf16 v[32:35], v[170:173], v[204:207], v[32:35]
	v_mfma_f32_16x16x32_bf16 v[20:23], v[162:165], v[212:215], v[20:23]
	v_mfma_f32_16x16x32_bf16 v[16:19], v[170:173], v[212:215], v[16:19]
	v_mfma_f32_16x16x32_bf16 v[4:7], v[162:165], v[220:223], v[4:7]
	v_mfma_f32_16x16x32_bf16 v[0:3], v[170:173], v[220:223], v[0:3]
	s_barrier
	s_setprio 0
	s_add_i32 s57, 0, 0x18000
	s_add_i32 s58, 0, 0x1c000
	v_add_u32_e32 v154, s57, v142
	v_add_u32_e32 v170, s58, v142
	ds_read_b128 v[136:139], v154
	ds_read_b128 v[146:149], v154 offset:1024
	ds_read_b128 v[150:153], v154 offset:2048
	ds_read_b128 v[154:157], v154 offset:3072
	ds_read_b128 v[158:161], v170
	ds_read_b128 v[162:165], v170 offset:1024
	ds_read_b128 v[166:169], v170 offset:2048
	ds_read_b128 v[170:173], v170 offset:3072
	s_mov_b32 m0, s10
	s_nop 0
	global_load_lds_dwordx4 v192, s[44:45]
	s_mov_b32 m0, s12
	s_nop 0
	global_load_lds_dwordx4 v196, s[44:45]
	s_add_u32 s44, s44, 0x80000
	s_addc_u32 s45, s45, 0
	s_mov_b32 m0, s13
	ds_read_b128 v[174:177], v144 offset:32768
	ds_read_b128 v[178:181], v144 offset:33792
	ds_read_b128 v[182:185], v144 offset:34816
	ds_read_b128 v[204:207], v144 offset:35840
	ds_read_b128 v[208:211], v144 offset:36864
	ds_read_b128 v[212:215], v144 offset:37888
	ds_read_b128 v[216:219], v144 offset:38912
	ds_read_b128 v[220:223], v144 offset:39936
	global_load_lds_dwordx4 v192, s[44:45]
	s_mov_b32 m0, s14
	s_nop 0
	global_load_lds_dwordx4 v196, s[44:45]
	s_waitcnt vmcnt(8)
	s_waitcnt lgkmcnt(0)
	s_setprio 1
	s_barrier
; #define PG8_STAGE(bufoff, gbase, voff) do { _Pragma("unroll") for (int _i = 0; _i < 2; ++_i) \
;         __builtin_amdgcn_global_load_lds((const unsigned*)((const char*)(gbase) + (voff)[_i]), (PG8_LAS unsigned*)(lds + (bufoff) + ldsw + _i * 8192), 16, 0, 0); } while (0)
; #define PG8_LDA(dst, b, h) do { _Pragma("unroll") for (int m = 0; m < 4; ++m) _Pragma("unroll") for (int k = 0; k < 2; ++k) dst[m][k] = *(const PG8_LAS bf16x8*)(lds + PG8_SA(b, h) + aoff + m * 2048 + k * 1024); } while (0)
; #define PG8_LDB(dst, b, h) do { _Pragma("unroll") for (int n = 0; n < 2; ++n) _Pragma("unroll") for (int k = 0; k < 2; ++k) dst[n][k] = *(const PG8_LAS bf16x8*)(lds + PG8_SB(b, h) + boff + n * 2048 + k * 1024); } while (0)
; #define PG8_MMA(ai, bj, At, Bt) do { __builtin_amdgcn_s_setprio(1); _Pragma("unroll") for (int m = 0; m < 4; ++m) _Pragma("unroll") for (int n = 0; n < 2; ++n) _Pragma("unroll") for (int k = 0; k < 2; ++k) \
;         acc[ai][bj][m][n] = __builtin_amdgcn_mfma_f32_16x16x32_bf16(Bt[n][k], At[m][k], acc[ai][bj][m][n], 0, 0, 0); __builtin_amdgcn_s_setprio(0); } while (0)
; #define PG8_WAIT_V(n) asm volatile("s_waitcnt vmcnt(" #n ")" ::: "memory")
; template <class Epi, class Sched, bool ALIGN_EPI = false, bool SP2 = false>
; __device__ __forceinline__ void gemm_phase(PG8_LAS unsigned char* lds, const Gemm g, const Sched& S, const Epi& E) {
;     ...
;             PG8_LDB(B0, 0, 0); PG8_LDB(B1, 0, 1); PG8_SCHED; PG8_LDA(At, 0, 0); PG8_STAGE(PG8_SA(1, 1), a1 + hstepA, voffA);
;             PG8_WAIT_V(8); PG8_WAIT_L(0); PG8_BAR; PG8_MMA(0, 0, At, B0); PG8_MMA(0, 1, At, B1); PG8_BAR; PG8_SCHED;
;             PG8_LDA(At, 0, 1); PG8_STAGE(PG8_SB(0, 0), b2, voffB); PG8_STAGE(PG8_SB(0, 1), b2 + hstepB, voffB); PG8_STAGE(PG8_SA(0, 0), a2, voffA);
;             PG8_WAIT_V(8); PG8_WAIT_L(0); PG8_BAR; PG8_MMA(1, 0, At, B0); PG8_MMA(1, 1, At, B1); PG8_BAR; PG8_SCHED;
;             PG8_LDB(B0, 1, 0); PG8_LDB(B1, 1, 1); PG8_SCHED; PG8_LDA(At, 1, 0); PG8_STAGE(PG8_SA(0, 1), a2 + hstepA, voffA);
;             PG8_WAIT_V(8); PG8_WAIT_L(0); PG8_BAR; PG8_MMA(0, 0, At, B0); PG8_MMA(0, 1, At, B1); PG8_BAR; PG8_SCHED;
;             PG8_LDA(At, 1, 1); PG8_STAGE(PG8_SB(1, 0), b3, voffB); PG8_STAGE(PG8_SB(1, 1), b3 + hstepB, voffB); PG8_STAGE(PG8_SA(1, 0), a3, voffA);
;             PG8_WAIT_V(8); PG8_WAIT_L(0); PG8_BAR; PG8_MMA(1, 0, At, B0); PG8_MMA(1, 1, At, B1); PG8_BAR; PG8_SCHED;
	v_mfma_f32_16x16x32_bf16 v[124:127], v[136:139], v[174:177], v[124:127]
	v_mfma_f32_16x16x32_bf16 v[120:123], v[150:153], v[174:177], v[120:123]
	v_mfma_f32_16x16x32_bf16 v[108:111], v[136:139], v[182:185], v[108:111]
	v_mfma_f32_16x16x32_bf16 v[104:107], v[150:153], v[182:185], v[104:107]
	v_mfma_f32_16x16x32_bf16 v[92:95], v[136:139], v[208:211], v[92:95]
	v_mfma_f32_16x16x32_bf16 v[88:91], v[150:153], v[208:211], v[88:91]
	v_mfma_f32_16x16x32_bf16 v[76:79], v[136:139], v[216:219], v[76:79]
	v_mfma_f32_16x16x32_bf16 v[72:75], v[150:153], v[216:219], v[72:75]
	v_mfma_f32_16x16x32_bf16 v[124:127], v[146:149], v[178:181], v[124:127]
	v_mfma_f32_16x16x32_bf16 v[120:123], v[154:157], v[178:181], v[120:123]
	v_mfma_f32_16x16x32_bf16 v[108:111], v[146:149], v[204:207], v[108:111]
	v_mfma_f32_16x16x32_bf16 v[104:107], v[154:157], v[204:207], v[104:107]
	v_mfma_f32_16x16x32_bf16 v[92:95], v[146:149], v[212:215], v[92:95]
	v_mfma_f32_16x16x32_bf16 v[88:91], v[154:157], v[212:215], v[88:91]
	v_mfma_f32_16x16x32_bf16 v[76:79], v[146:149], v[220:223], v[76:79]
	v_mfma_f32_16x16x32_bf16 v[72:75], v[154:157], v[220:223], v[72:75]
	v_mfma_f32_16x16x32_bf16 v[116:119], v[158:161], v[174:177], v[116:119]
	v_mfma_f32_16x16x32_bf16 v[112:115], v[166:169], v[174:177], v[112:115]
	v_mfma_f32_16x16x32_bf16 v[100:103], v[158:161], v[182:185], v[100:103]
	v_mfma_f32_16x16x32_bf16 v[96:99], v[166:169], v[182:185], v[96:99]
	v_mfma_f32_16x16x32_bf16 v[84:87], v[158:161], v[208:211], v[84:87]
	v_mfma_f32_16x16x32_bf16 v[80:83], v[166:169], v[208:211], v[80:83]
	v_mfma_f32_16x16x32_bf16 v[68:71], v[158:161], v[216:219], v[68:71]
	v_mfma_f32_16x16x32_bf16 v[64:67], v[166:169], v[216:219], v[64:67]
	v_mfma_f32_16x16x32_bf16 v[116:119], v[162:165], v[178:181], v[116:119]
	v_mfma_f32_16x16x32_bf16 v[112:115], v[170:173], v[178:181], v[112:115]
	v_mfma_f32_16x16x32_bf16 v[100:103], v[162:165], v[204:207], v[100:103]
	v_mfma_f32_16x16x32_bf16 v[96:99], v[170:173], v[204:207], v[96:99]
	v_mfma_f32_16x16x32_bf16 v[84:87], v[162:165], v[212:215], v[84:87]
	v_mfma_f32_16x16x32_bf16 v[80:83], v[170:173], v[212:215], v[80:83]
	v_mfma_f32_16x16x32_bf16 v[68:71], v[162:165], v[220:223], v[68:71]
	v_mfma_f32_16x16x32_bf16 v[64:67], v[170:173], v[220:223], v[64:67]
	s_barrier
	s_setprio 0
	s_add_u32 s44, s42, 0x8000
	s_addc_u32 s45, s43, 0
	s_add_i32 s57, s57, s2
	s_mov_b32 m0, s57
	ds_read_b128 v[174:177], v144 offset:49152
	ds_read_b128 v[178:181], v144 offset:50176
	ds_read_b128 v[182:185], v144 offset:51200
	ds_read_b128 v[204:207], v144 offset:52224
	ds_read_b128 v[208:211], v144 offset:53248
	ds_read_b128 v[212:215], v144 offset:54272
	ds_read_b128 v[216:219], v144 offset:55296
	ds_read_b128 v[220:223], v144 offset:56320
	global_load_lds_dwordx4 v194, s[44:45]
	s_add_i32 m0, s57, 0x2000
	s_add_u32 s42, s42, 0xc000
	s_addc_u32 s43, s43, 0
	global_load_lds_dwordx4 v198, s[44:45]
	s_add_i32 s44, s58, s2
	s_mov_b32 m0, s44
	s_nop 0
	global_load_lds_dwordx4 v194, s[42:43]
	s_add_i32 m0, s44, 0x2000
	s_nop 0
	global_load_lds_dwordx4 v198, s[42:43]
	s_waitcnt vmcnt(6)
	s_waitcnt lgkmcnt(0)
	s_setprio 1
	s_barrier
	v_mfma_f32_16x16x32_bf16 v[60:63], v[136:139], v[174:177], v[60:63]
	v_mfma_f32_16x16x32_bf16 v[56:59], v[150:153], v[174:177], v[56:59]
	v_mfma_f32_16x16x32_bf16 v[44:47], v[136:139], v[182:185], v[44:47]
	v_mfma_f32_16x16x32_bf16 v[40:43], v[150:153], v[182:185], v[40:43]
	v_mfma_f32_16x16x32_bf16 v[28:31], v[136:139], v[208:211], v[28:31]
	v_mfma_f32_16x16x32_bf16 v[24:27], v[150:153], v[208:211], v[24:27]
	v_mfma_f32_16x16x32_bf16 v[12:15], v[136:139], v[216:219], v[12:15]
	v_mfma_f32_16x16x32_bf16 v[8:11], v[150:153], v[216:219], v[8:11]
	v_mfma_f32_16x16x32_bf16 v[60:63], v[146:149], v[178:181], v[60:63]
	v_mfma_f32_16x16x32_bf16 v[56:59], v[154:157], v[178:181], v[56:59]
	v_mfma_f32_16x16x32_bf16 v[44:47], v[146:149], v[204:207], v[44:47]
	v_mfma_f32_16x16x32_bf16 v[40:43], v[154:157], v[204:207], v[40:43]
	v_mfma_f32_16x16x32_bf16 v[28:31], v[146:149], v[212:215], v[28:31]
	v_mfma_f32_16x16x32_bf16 v[24:27], v[154:157], v[212:215], v[24:27]
	v_mfma_f32_16x16x32_bf16 v[12:15], v[146:149], v[220:223], v[12:15]
	v_mfma_f32_16x16x32_bf16 v[8:11], v[154:157], v[220:223], v[8:11]
	v_mfma_f32_16x16x32_bf16 v[52:55], v[158:161], v[174:177], v[52:55]
	v_mfma_f32_16x16x32_bf16 v[48:51], v[166:169], v[174:177], v[48:51]
	v_mfma_f32_16x16x32_bf16 v[36:39], v[158:161], v[182:185], v[36:39]
	v_mfma_f32_16x16x32_bf16 v[32:35], v[166:169], v[182:185], v[32:35]
	v_mfma_f32_16x16x32_bf16 v[20:23], v[158:161], v[208:211], v[20:23]
	v_mfma_f32_16x16x32_bf16 v[16:19], v[166:169], v[208:211], v[16:19]
	v_mfma_f32_16x16x32_bf16 v[4:7], v[158:161], v[216:219], v[4:7]
	v_mfma_f32_16x16x32_bf16 v[0:3], v[166:169], v[216:219], v[0:3]
	v_mfma_f32_16x16x32_bf16 v[52:55], v[162:165], v[178:181], v[52:55]
	v_mfma_f32_16x16x32_bf16 v[48:51], v[170:173], v[178:181], v[48:51]
	v_mfma_f32_16x16x32_bf16 v[36:39], v[162:165], v[204:207], v[36:39]
	v_mfma_f32_16x16x32_bf16 v[32:35], v[170:173], v[204:207], v[32:35]
	v_mfma_f32_16x16x32_bf16 v[20:23], v[162:165], v[212:215], v[20:23]
	v_mfma_f32_16x16x32_bf16 v[16:19], v[170:173], v[212:215], v[16:19]
	v_mfma_f32_16x16x32_bf16 v[4:7], v[162:165], v[220:223], v[4:7]
	v_mfma_f32_16x16x32_bf16 v[0:3], v[170:173], v[220:223], v[0:3]
	s_barrier
	s_setprio 0
	s_add_i32 s56, s56, 2
	s_add_u32 s54, s54, 0x10000
	s_addc_u32 s55, s55, 0
	s_add_u32 s40, s40, 0x100
	s_addc_u32 s41, s41, 0
	s_cmp_gt_u32 s56, 29
	s_cbranch_scc1 .Lpeel_exit_0

; __device__ __forceinline__ unsigned cvt_pk_bf16(float lo, float hi) { unsigned r; asm volatile("v_cvt_pk_bf16_f32 %0, %1, %2" : "=v"(r) : "v"(lo), "v"(hi)); return r; }
; __device__ __forceinline__ float silu_mul(float g, float u) { return g * __builtin_amdgcn_rcpf(1.0f + __builtin_amdgcn_exp2f(-1.4426950408889634f * g)) * u; }
;     __device__ __forceinline__ void operator()(const f32x4 (&acc)[2][2][4][2], const Unit& u, int wr, int wc, int fr, int fq) const {
;         const int row0 = u.pm * BM + wr * 64 + fr, j0 = u.pn * HALF + wc * 32 + 8 * fq;
;         float rs[2][4];
; #pragma unroll
;         for (int ai = 0; ai < 2; ++ai)
; #pragma unroll
;             for (int m = 0; m < 4; ++m) rs[ai][m] = ss[row0 + ai * HALF + m * 16];
;         __builtin_amdgcn_sched_barrier(0);
; #pragma unroll
;         for (int ai = 0; ai < 2; ++ai)
; #pragma unroll
;             for (int m = 0; m < 4; ++m) {
;                 const int row = row0 + ai * HALF + m * 16;
;                 const float r = __builtin_amdgcn_rsqf(rs[ai][m] * (1.0f / DM) + EPSN);
;                 const f32x4 g0 = acc[ai][0][m][0] * r, g1 = acc[ai][0][m][1] * r, u0 = acc[ai][1][m][0] * r, u1 = acc[ai][1][m][1] * r;
;                 u32x4 w;
;                 w.x = cvt_pk_bf16(silu_mul(g0[0], u0[0]), silu_mul(g0[1], u0[1])); w.y = cvt_pk_bf16(silu_mul(g0[2], u0[2]), silu_mul(g0[3], u0[3]));
;                 w.z = cvt_pk_bf16(silu_mul(g1[0], u1[0]), silu_mul(g1[1], u1[1])); w.w = cvt_pk_bf16(silu_mul(g1[2], u1[2]), silu_mul(g1[3], u1[3]));
;                 *(u32x4*)(act + (((size_t)u.pm * (DFF / 64) + (u.pn * 2 + (wc >> 1))) * 256 + (row - u.pm * BM)) * 64 + (wc & 1) * 32 + 8 * fq) = w;
.LBB0_280:
	v_and_b32_e32 v223, 15, v202
	s_lshr_b32 s98, s10, 1
	s_add_i32 s98, s98, 0x20000
	v_lshl_add_u32 v223, v223, 2, s98
	s_lshl_b32 s27, s38, 8
	v_add_u32_e32 v136, s27, v128
	v_or_b32_e32 v140, 16, v136
	v_ashrrev_i32_e32 v137, 31, v136
	v_ashrrev_i32_e32 v141, 31, v140
	v_lshl_add_u64 v[148:149], v[136:137], 2, s[18:19]
	v_lshl_add_u64 v[138:139], v[140:141], 2, s[18:19]
	v_or_b32_e32 v138, 32, v136
	v_ashrrev_i32_e32 v139, 31, v138
	v_or_b32_e32 v136, 48, v136
	v_lshl_add_u64 v[146:147], v[138:139], 2, s[18:19]
	v_ashrrev_i32_e32 v137, 31, v136
	v_lshl_add_u64 v[146:147], v[136:137], 2, s[18:19]
	s_nop 0
	ds_read_b32 v150, v223
	ds_read_b32 v152, v223 offset:64
	ds_read_b32 v153, v223 offset:128
	ds_read_b32 v147, v223 offset:192
	ds_read_b32 v146, v223 offset:256
	ds_read_b32 v141, v223 offset:320
	ds_read_b32 v139, v223 offset:384
	ds_read_b32 v137, v223 offset:448
	s_waitcnt lgkmcnt(0)
	s_mov_b32 s100, 0xbfb8aa3b
	s_mov_b32 s101, 0xbfb8aa3b
	v_fmamk_f32 v148, v150, 0x3a000000, v145
	v_rsq_f32_e32 v148, v148
	s_lshl_b32 s39, s39, 1
	s_or_b32 s39, s39, s48
	s_mul_hi_i32 s29, s38, 0x56
	v_pk_mul_f32 v[124:125], v[124:125], v[148:149] op_sel_hi:[1,0]
	v_pk_mul_f32 v[150:151], v[114:115], v[148:149] op_sel_hi:[1,0]
	v_pk_mul_f32 v[114:115], v[112:113], v[148:149] op_sel_hi:[1,0]
	v_pk_mul_f32 v[116:117], v[116:117], v[148:149] op_sel_hi:[1,0]
	v_pk_mul_f32 v[126:127], v[126:127], v[148:149] op_sel_hi:[1,0]
	v_pk_mul_f32 v[118:119], v[118:119], v[148:149] op_sel_hi:[1,0]
	v_pk_mul_f32 v[120:121], v[120:121], v[148:149] op_sel_hi:[1,0]
	v_pk_mul_f32 v[122:123], v[122:123], v[148:149] op_sel_hi:[1,0]
	v_pk_mul_f32 v[154:155], v[124:125], s[100:101]
	v_pk_mul_f32 v[156:157], v[126:127], s[100:101]
	v_exp_f32_e32 v154, v154
	v_exp_f32_e32 v155, v155
	v_exp_f32_e32 v156, v156
	v_exp_f32_e32 v157, v157
	v_pk_add_f32 v[154:155], v[154:155], 1.0 op_sel_hi:[1,0]
	v_pk_add_f32 v[156:157], v[156:157], 1.0 op_sel_hi:[1,0]
	v_rcp_f32_e32 v154, v154
	v_rcp_f32_e32 v155, v155
	v_rcp_f32_e32 v156, v156
	v_rcp_f32_e32 v157, v157
	v_pk_mul_f32 v[154:155], v[124:125], v[154:155]
	v_pk_mul_f32 v[156:157], v[126:127], v[156:157]
	v_pk_mul_f32 v[154:155], v[116:117], v[154:155]
	v_pk_mul_f32 v[156:157], v[118:119], v[156:157]
	v_pk_mul_f32 v[158:159], v[120:121], s[100:101]
	v_pk_mul_f32 v[160:161], v[122:123], s[100:101]
	v_exp_f32_e32 v158, v158
	v_exp_f32_e32 v159, v159
	v_exp_f32_e32 v160, v160
	v_exp_f32_e32 v161, v161
	v_pk_add_f32 v[158:159], v[158:159], 1.0 op_sel_hi:[1,0]
	v_pk_add_f32 v[160:161], v[160:161], 1.0 op_sel_hi:[1,0]
	v_rcp_f32_e32 v158, v158
	v_rcp_f32_e32 v159, v159
	v_rcp_f32_e32 v160, v160
	v_rcp_f32_e32 v161, v161
	v_pk_mul_f32 v[158:159], v[120:121], v[158:159]
	v_pk_mul_f32 v[160:161], v[122:123], v[160:161]
	v_pk_mul_f32 v[158:159], v[114:115], v[158:159]
	v_pk_mul_f32 v[160:161], v[150:151], v[160:161]
	v_cvt_pk_bf16_f32 v112, v154, v155
	v_cvt_pk_bf16_f32 v113, v156, v157
	v_cvt_pk_bf16_f32 v114, v158, v159
	v_cvt_pk_bf16_f32 v115, v160, v161
	s_mulk_i32 s38, 0x56
	s_ashr_i32 s40, s39, 31
	s_add_u32 s38, s38, s39
	s_addc_u32 s39, s29, s40
	s_lshl_b64 s[38:39], s[38:39], 15
	s_add_u32 s38, s4, s38
	s_addc_u32 s39, s5, s39
	s_nop 0
	s_nop 0
	v_lshl_add_u64 v[116:117], s[38:39], 0, v[130:131]
	v_lshl_add_u64 v[116:117], v[116:117], 0, s[22:23]
	v_lshl_add_u64 v[116:117], v[116:117], 0, v[200:201]
	global_store_dwordx4 v[116:117], v[112:115], off
	s_nop 1
	v_fmamk_f32 v112, v152, 0x3a000000, v145
	v_rsq_f32_e32 v112, v112
	s_nop 0
	v_pk_mul_f32 v[108:109], v[108:109], v[112:113] op_sel_hi:[1,0]
	v_pk_mul_f32 v[114:115], v[98:99], v[112:113] op_sel_hi:[1,0]
	v_pk_mul_f32 v[98:99], v[96:97], v[112:113] op_sel_hi:[1,0]
	v_pk_mul_f32 v[100:101], v[100:101], v[112:113] op_sel_hi:[1,0]
	v_pk_mul_f32 v[110:111], v[110:111], v[112:113] op_sel_hi:[1,0]
	v_pk_mul_f32 v[102:103], v[102:103], v[112:113] op_sel_hi:[1,0]
	v_pk_mul_f32 v[104:105], v[104:105], v[112:113] op_sel_hi:[1,0]
	v_pk_mul_f32 v[106:107], v[106:107], v[112:113] op_sel_hi:[1,0]
	v_pk_mul_f32 v[154:155], v[108:109], s[100:101]
	v_pk_mul_f32 v[156:157], v[110:111], s[100:101]
	v_exp_f32_e32 v154, v154
	v_exp_f32_e32 v155, v155
	v_exp_f32_e32 v156, v156
	v_exp_f32_e32 v157, v157
	v_pk_add_f32 v[154:155], v[154:155], 1.0 op_sel_hi:[1,0]
	v_pk_add_f32 v[156:157], v[156:157], 1.0 op_sel_hi:[1,0]
	v_rcp_f32_e32 v154, v154
	v_rcp_f32_e32 v155, v155
	v_rcp_f32_e32 v156, v156
	v_rcp_f32_e32 v157, v157
	v_pk_mul_f32 v[154:155], v[108:109], v[154:155]
	v_pk_mul_f32 v[156:157], v[110:111], v[156:157]
	v_pk_mul_f32 v[154:155], v[100:101], v[154:155]
	v_pk_mul_f32 v[156:157], v[102:103], v[156:157]
	v_pk_mul_f32 v[158:159], v[104:105], s[100:101]
	v_pk_mul_f32 v[160:161], v[106:107], s[100:101]
	v_exp_f32_e32 v158, v158
	v_exp_f32_e32 v159, v159
	v_exp_f32_e32 v160, v160
	v_exp_f32_e32 v161, v161
	v_pk_add_f32 v[158:159], v[158:159], 1.0 op_sel_hi:[1,0]
	v_pk_add_f32 v[160:161], v[160:161], 1.0 op_sel_hi:[1,0]
	v_rcp_f32_e32 v158, v158
	v_rcp_f32_e32 v159, v159
	v_rcp_f32_e32 v160, v160
	v_rcp_f32_e32 v161, v161
	v_pk_mul_f32 v[158:159], v[104:105], v[158:159]
	v_pk_mul_f32 v[160:161], v[106:107], v[160:161]
	v_pk_mul_f32 v[158:159], v[98:99], v[158:159]
	v_pk_mul_f32 v[160:161], v[114:115], v[160:161]
	v_cvt_pk_bf16_f32 v96, v154, v155
	v_cvt_pk_bf16_f32 v97, v156, v157
	v_cvt_pk_bf16_f32 v98, v158, v159
	v_cvt_pk_bf16_f32 v99, v160, v161
	s_nop 0
	s_nop 0
	s_nop 0
	s_nop 0
	v_subrev_u32_e32 v100, s27, v140
	v_ashrrev_i32_e32 v101, 31, v100
	v_lshlrev_b64 v[100:101], 7, v[100:101]
	v_lshl_add_u64 v[100:101], s[38:39], 0, v[100:101]
	v_lshl_add_u64 v[100:101], v[100:101], 0, s[22:23]
; __device__ __forceinline__ unsigned cvt_pk_bf16(float lo, float hi) { unsigned r; asm volatile("v_cvt_pk_bf16_f32 %0, %1, %2" : "=v"(r) : "v"(lo), "v"(hi)); return r; }
; __device__ __forceinline__ float silu_mul(float g, float u) { return g * __builtin_amdgcn_rcpf(1.0f + __builtin_amdgcn_exp2f(-1.4426950408889634f * g)) * u; }
;     __device__ __forceinline__ void operator()(const f32x4 (&acc)[2][2][4][2], const Unit& u, int wr, int wc, int fr, int fq) const {
;     ...
;             for (int m = 0; m < 4; ++m) {
;                 const int row = row0 + ai * HALF + m * 16;
;                 const float r = __builtin_amdgcn_rsqf(rs[ai][m] * (1.0f / DM) + EPSN);
;                 const f32x4 g0 = acc[ai][0][m][0] * r, g1 = acc[ai][0][m][1] * r, u0 = acc[ai][1][m][0] * r, u1 = acc[ai][1][m][1] * r;
;                 u32x4 w;
;                 w.x = cvt_pk_bf16(silu_mul(g0[0], u0[0]), silu_mul(g0[1], u0[1])); w.y = cvt_pk_bf16(silu_mul(g0[2], u0[2]), silu_mul(g0[3], u0[3]));
;                 w.z = cvt_pk_bf16(silu_mul(g1[0], u1[0]), silu_mul(g1[1], u1[1])); w.w = cvt_pk_bf16(silu_mul(g1[2], u1[2]), silu_mul(g1[3], u1[3]));
;                 *(u32x4*)(act + (((size_t)u.pm * (DFF / 64) + (u.pn * 2 + (wc >> 1))) * 256 + (row - u.pm * BM)) * 64 + (wc & 1) * 32 + 8 * fq) = w;
	v_lshl_add_u64 v[100:101], v[100:101], 0, v[200:201]
	global_store_dwordx4 v[100:101], v[96:99], off
	s_nop 1
	v_fmamk_f32 v96, v153, 0x3a000000, v145
	v_rsq_f32_e32 v96, v96
	s_nop 0
	v_pk_mul_f32 v[92:93], v[92:93], v[96:97] op_sel_hi:[1,0]
	v_pk_mul_f32 v[98:99], v[82:83], v[96:97] op_sel_hi:[1,0]
	v_pk_mul_f32 v[82:83], v[80:81], v[96:97] op_sel_hi:[1,0]
	v_pk_mul_f32 v[84:85], v[84:85], v[96:97] op_sel_hi:[1,0]
	v_pk_mul_f32 v[94:95], v[94:95], v[96:97] op_sel_hi:[1,0]
	v_pk_mul_f32 v[86:87], v[86:87], v[96:97] op_sel_hi:[1,0]
	v_pk_mul_f32 v[88:89], v[88:89], v[96:97] op_sel_hi:[1,0]
	v_pk_mul_f32 v[90:91], v[90:91], v[96:97] op_sel_hi:[1,0]
	v_pk_mul_f32 v[154:155], v[92:93], s[100:101]
	v_pk_mul_f32 v[156:157], v[94:95], s[100:101]
	v_exp_f32_e32 v154, v154
	v_exp_f32_e32 v155, v155
	v_exp_f32_e32 v156, v156
	v_exp_f32_e32 v157, v157
	v_pk_add_f32 v[154:155], v[154:155], 1.0 op_sel_hi:[1,0]
	v_pk_add_f32 v[156:157], v[156:157], 1.0 op_sel_hi:[1,0]
	v_rcp_f32_e32 v154, v154
	v_rcp_f32_e32 v155, v155
	v_rcp_f32_e32 v156, v156
	v_rcp_f32_e32 v157, v157
	v_pk_mul_f32 v[154:155], v[92:93], v[154:155]
	v_pk_mul_f32 v[156:157], v[94:95], v[156:157]
	v_pk_mul_f32 v[154:155], v[84:85], v[154:155]
	v_pk_mul_f32 v[156:157], v[86:87], v[156:157]
	v_pk_mul_f32 v[158:159], v[88:89], s[100:101]
	v_pk_mul_f32 v[160:161], v[90:91], s[100:101]
	v_exp_f32_e32 v158, v158
	v_exp_f32_e32 v159, v159
	v_exp_f32_e32 v160, v160
	v_exp_f32_e32 v161, v161
	v_pk_add_f32 v[158:159], v[158:159], 1.0 op_sel_hi:[1,0]
	v_pk_add_f32 v[160:161], v[160:161], 1.0 op_sel_hi:[1,0]
	v_rcp_f32_e32 v158, v158
	v_rcp_f32_e32 v159, v159
	v_rcp_f32_e32 v160, v160
	v_rcp_f32_e32 v161, v161
	v_pk_mul_f32 v[158:159], v[88:89], v[158:159]
	v_pk_mul_f32 v[160:161], v[90:91], v[160:161]
	v_pk_mul_f32 v[158:159], v[82:83], v[158:159]
	v_pk_mul_f32 v[160:161], v[98:99], v[160:161]
	v_cvt_pk_bf16_f32 v80, v154, v155
	v_cvt_pk_bf16_f32 v81, v156, v157
	v_cvt_pk_bf16_f32 v82, v158, v159
	v_cvt_pk_bf16_f32 v83, v160, v161
	s_nop 0
	s_nop 0
	s_nop 0
	s_nop 0
	v_subrev_u32_e32 v84, s27, v138
	v_ashrrev_i32_e32 v85, 31, v84
	v_lshlrev_b64 v[84:85], 7, v[84:85]
	v_lshl_add_u64 v[84:85], s[38:39], 0, v[84:85]
	v_lshl_add_u64 v[84:85], v[84:85], 0, s[22:23]
	v_lshl_add_u64 v[84:85], v[84:85], 0, v[200:201]
	global_store_dwordx4 v[84:85], v[80:83], off
	s_nop 1
	v_fmamk_f32 v80, v147, 0x3a000000, v145
	v_rsq_f32_e32 v80, v80
	s_nop 0
	v_pk_mul_f32 v[76:77], v[76:77], v[80:81] op_sel_hi:[1,0]
	v_pk_mul_f32 v[82:83], v[66:67], v[80:81] op_sel_hi:[1,0]
	v_pk_mul_f32 v[66:67], v[64:65], v[80:81] op_sel_hi:[1,0]
	v_pk_mul_f32 v[68:69], v[68:69], v[80:81] op_sel_hi:[1,0]
	v_pk_mul_f32 v[78:79], v[78:79], v[80:81] op_sel_hi:[1,0]
	v_pk_mul_f32 v[70:71], v[70:71], v[80:81] op_sel_hi:[1,0]
	v_pk_mul_f32 v[72:73], v[72:73], v[80:81] op_sel_hi:[1,0]
	v_pk_mul_f32 v[74:75], v[74:75], v[80:81] op_sel_hi:[1,0]
	v_pk_mul_f32 v[154:155], v[76:77], s[100:101]
	v_pk_mul_f32 v[156:157], v[78:79], s[100:101]
	v_exp_f32_e32 v154, v154
	v_exp_f32_e32 v155, v155
	v_exp_f32_e32 v156, v156
	v_exp_f32_e32 v157, v157
	v_pk_add_f32 v[154:155], v[154:155], 1.0 op_sel_hi:[1,0]
	v_pk_add_f32 v[156:157], v[156:157], 1.0 op_sel_hi:[1,0]
	v_rcp_f32_e32 v154, v154
	v_rcp_f32_e32 v155, v155
	v_rcp_f32_e32 v156, v156
	v_rcp_f32_e32 v157, v157
	v_pk_mul_f32 v[154:155], v[76:77], v[154:155]
	v_pk_mul_f32 v[156:157], v[78:79], v[156:157]
	v_pk_mul_f32 v[154:155], v[68:69], v[154:155]
	v_pk_mul_f32 v[156:157], v[70:71], v[156:157]
	v_pk_mul_f32 v[158:159], v[72:73], s[100:101]
	v_pk_mul_f32 v[160:161], v[74:75], s[100:101]
	v_exp_f32_e32 v158, v158
	v_exp_f32_e32 v159, v159
	v_exp_f32_e32 v160, v160
	v_exp_f32_e32 v161, v161
	v_pk_add_f32 v[158:159], v[158:159], 1.0 op_sel_hi:[1,0]
	v_pk_add_f32 v[160:161], v[160:161], 1.0 op_sel_hi:[1,0]
	v_rcp_f32_e32 v158, v158
	v_rcp_f32_e32 v159, v159
	v_rcp_f32_e32 v160, v160
	v_rcp_f32_e32 v161, v161
	v_pk_mul_f32 v[158:159], v[72:73], v[158:159]
	v_pk_mul_f32 v[160:161], v[74:75], v[160:161]
	v_pk_mul_f32 v[158:159], v[66:67], v[158:159]
	v_pk_mul_f32 v[160:161], v[82:83], v[160:161]
	v_cvt_pk_bf16_f32 v64, v154, v155
	v_cvt_pk_bf16_f32 v65, v156, v157
	v_cvt_pk_bf16_f32 v66, v158, v159
	v_cvt_pk_bf16_f32 v67, v160, v161
	s_nop 0
	s_nop 0
	s_nop 0
	s_nop 0
	v_subrev_u32_e32 v68, s27, v136
	v_ashrrev_i32_e32 v69, 31, v68
	v_lshlrev_b64 v[68:69], 7, v[68:69]
	v_lshl_add_u64 v[68:69], s[38:39], 0, v[68:69]
	v_lshl_add_u64 v[68:69], v[68:69], 0, s[22:23]
	v_lshl_add_u64 v[68:69], v[68:69], 0, v[200:201]
	global_store_dwordx4 v[68:69], v[64:67], off
	s_nop 1
	v_fmamk_f32 v64, v146, 0x3a000000, v145
	v_rsq_f32_e32 v64, v64
	s_nop 0
	v_pk_mul_f32 v[60:61], v[60:61], v[64:65] op_sel_hi:[1,0]
	v_pk_mul_f32 v[66:67], v[50:51], v[64:65] op_sel_hi:[1,0]
	v_pk_mul_f32 v[50:51], v[48:49], v[64:65] op_sel_hi:[1,0]
	v_pk_mul_f32 v[52:53], v[52:53], v[64:65] op_sel_hi:[1,0]
	v_pk_mul_f32 v[62:63], v[62:63], v[64:65] op_sel_hi:[1,0]
	v_pk_mul_f32 v[54:55], v[54:55], v[64:65] op_sel_hi:[1,0]
	v_pk_mul_f32 v[56:57], v[56:57], v[64:65] op_sel_hi:[1,0]
	v_pk_mul_f32 v[58:59], v[58:59], v[64:65] op_sel_hi:[1,0]
	v_pk_mul_f32 v[154:155], v[60:61], s[100:101]
	v_pk_mul_f32 v[156:157], v[62:63], s[100:101]
	v_exp_f32_e32 v154, v154
	v_exp_f32_e32 v155, v155
	v_exp_f32_e32 v156, v156
	v_exp_f32_e32 v157, v157
	v_pk_add_f32 v[154:155], v[154:155], 1.0 op_sel_hi:[1,0]
	v_pk_add_f32 v[156:157], v[156:157], 1.0 op_sel_hi:[1,0]
	v_rcp_f32_e32 v154, v154
	v_rcp_f32_e32 v155, v155
	v_rcp_f32_e32 v156, v156
	v_rcp_f32_e32 v157, v157
	v_pk_mul_f32 v[154:155], v[60:61], v[154:155]
	v_pk_mul_f32 v[156:157], v[62:63], v[156:157]
; __device__ __forceinline__ unsigned cvt_pk_bf16(float lo, float hi) { unsigned r; asm volatile("v_cvt_pk_bf16_f32 %0, %1, %2" : "=v"(r) : "v"(lo), "v"(hi)); return r; }
; __device__ __forceinline__ float silu_mul(float g, float u) { return g * __builtin_amdgcn_rcpf(1.0f + __builtin_amdgcn_exp2f(-1.4426950408889634f * g)) * u; }
;     __device__ __forceinline__ void operator()(const f32x4 (&acc)[2][2][4][2], const Unit& u, int wr, int wc, int fr, int fq) const {
;     ...
;             for (int m = 0; m < 4; ++m) {
;                 const int row = row0 + ai * HALF + m * 16;
;                 const float r = __builtin_amdgcn_rsqf(rs[ai][m] * (1.0f / DM) + EPSN);
;                 const f32x4 g0 = acc[ai][0][m][0] * r, g1 = acc[ai][0][m][1] * r, u0 = acc[ai][1][m][0] * r, u1 = acc[ai][1][m][1] * r;
;                 u32x4 w;
;                 w.x = cvt_pk_bf16(silu_mul(g0[0], u0[0]), silu_mul(g0[1], u0[1])); w.y = cvt_pk_bf16(silu_mul(g0[2], u0[2]), silu_mul(g0[3], u0[3]));
;                 w.z = cvt_pk_bf16(silu_mul(g1[0], u1[0]), silu_mul(g1[1], u1[1])); w.w = cvt_pk_bf16(silu_mul(g1[2], u1[2]), silu_mul(g1[3], u1[3]));
;                 *(u32x4*)(act + (((size_t)u.pm * (DFF / 64) + (u.pn * 2 + (wc >> 1))) * 256 + (row - u.pm * BM)) * 64 + (wc & 1) * 32 + 8 * fq) = w;
	v_pk_mul_f32 v[154:155], v[52:53], v[154:155]
	v_pk_mul_f32 v[156:157], v[54:55], v[156:157]
	v_pk_mul_f32 v[158:159], v[56:57], s[100:101]
	v_pk_mul_f32 v[160:161], v[58:59], s[100:101]
	v_exp_f32_e32 v158, v158
	v_exp_f32_e32 v159, v159
	v_exp_f32_e32 v160, v160
	v_exp_f32_e32 v161, v161
	v_pk_add_f32 v[158:159], v[158:159], 1.0 op_sel_hi:[1,0]
	v_pk_add_f32 v[160:161], v[160:161], 1.0 op_sel_hi:[1,0]
	v_rcp_f32_e32 v158, v158
	v_rcp_f32_e32 v159, v159
	v_rcp_f32_e32 v160, v160
	v_rcp_f32_e32 v161, v161
	v_pk_mul_f32 v[158:159], v[56:57], v[158:159]
	v_pk_mul_f32 v[160:161], v[58:59], v[160:161]
	v_pk_mul_f32 v[158:159], v[50:51], v[158:159]
	v_pk_mul_f32 v[160:161], v[66:67], v[160:161]
	v_cvt_pk_bf16_f32 v48, v154, v155
	v_cvt_pk_bf16_f32 v49, v156, v157
	v_cvt_pk_bf16_f32 v50, v158, v159
	v_cvt_pk_bf16_f32 v51, v160, v161
	v_mov_b32_e32 v53, v201
	s_nop 0
	s_nop 0
	s_nop 0
	s_nop 0
	v_add_u32_e32 v52, 0x80, v128
	v_lshlrev_b64 v[52:53], 7, v[52:53]
	v_lshl_add_u64 v[52:53], s[38:39], 0, v[52:53]
	v_lshl_add_u64 v[52:53], v[52:53], 0, s[22:23]
	v_lshl_add_u64 v[52:53], v[52:53], 0, v[200:201]
	global_store_dwordx4 v[52:53], v[48:51], off
	s_nop 1
	v_fmamk_f32 v48, v141, 0x3a000000, v145
	v_rsq_f32_e32 v48, v48
	s_nop 0
	v_pk_mul_f32 v[44:45], v[44:45], v[48:49] op_sel_hi:[1,0]
	v_pk_mul_f32 v[50:51], v[34:35], v[48:49] op_sel_hi:[1,0]
	v_pk_mul_f32 v[34:35], v[32:33], v[48:49] op_sel_hi:[1,0]
	v_pk_mul_f32 v[36:37], v[36:37], v[48:49] op_sel_hi:[1,0]
	v_pk_mul_f32 v[46:47], v[46:47], v[48:49] op_sel_hi:[1,0]
	v_pk_mul_f32 v[38:39], v[38:39], v[48:49] op_sel_hi:[1,0]
	v_pk_mul_f32 v[40:41], v[40:41], v[48:49] op_sel_hi:[1,0]
	v_pk_mul_f32 v[42:43], v[42:43], v[48:49] op_sel_hi:[1,0]
	v_pk_mul_f32 v[154:155], v[44:45], s[100:101]
	v_pk_mul_f32 v[156:157], v[46:47], s[100:101]
	v_exp_f32_e32 v154, v154
	v_exp_f32_e32 v155, v155
	v_exp_f32_e32 v156, v156
	v_exp_f32_e32 v157, v157
	v_pk_add_f32 v[154:155], v[154:155], 1.0 op_sel_hi:[1,0]
	v_pk_add_f32 v[156:157], v[156:157], 1.0 op_sel_hi:[1,0]
	v_rcp_f32_e32 v154, v154
	v_rcp_f32_e32 v155, v155
	v_rcp_f32_e32 v156, v156
	v_rcp_f32_e32 v157, v157
	v_pk_mul_f32 v[154:155], v[44:45], v[154:155]
	v_pk_mul_f32 v[156:157], v[46:47], v[156:157]
	v_pk_mul_f32 v[154:155], v[36:37], v[154:155]
	v_pk_mul_f32 v[156:157], v[38:39], v[156:157]
	v_pk_mul_f32 v[158:159], v[40:41], s[100:101]
	v_pk_mul_f32 v[160:161], v[42:43], s[100:101]
	v_exp_f32_e32 v158, v158
	v_exp_f32_e32 v159, v159
	v_exp_f32_e32 v160, v160
	v_exp_f32_e32 v161, v161
	v_pk_add_f32 v[158:159], v[158:159], 1.0 op_sel_hi:[1,0]
	v_pk_add_f32 v[160:161], v[160:161], 1.0 op_sel_hi:[1,0]
	v_rcp_f32_e32 v158, v158
	v_rcp_f32_e32 v159, v159
	v_rcp_f32_e32 v160, v160
	v_rcp_f32_e32 v161, v161
	v_pk_mul_f32 v[158:159], v[40:41], v[158:159]
	v_pk_mul_f32 v[160:161], v[42:43], v[160:161]
	v_pk_mul_f32 v[158:159], v[34:35], v[158:159]
	v_pk_mul_f32 v[160:161], v[50:51], v[160:161]
	v_cvt_pk_bf16_f32 v32, v154, v155
	v_cvt_pk_bf16_f32 v33, v156, v157
	v_cvt_pk_bf16_f32 v34, v158, v159
	v_cvt_pk_bf16_f32 v35, v160, v161
	v_mov_b32_e32 v37, v201
	s_nop 0
	s_nop 0
	s_nop 0
	s_nop 0
	v_add_u32_e32 v36, 0x90, v128
	v_lshlrev_b64 v[36:37], 7, v[36:37]
	v_lshl_add_u64 v[36:37], s[38:39], 0, v[36:37]
	v_lshl_add_u64 v[36:37], v[36:37], 0, s[22:23]
	v_lshl_add_u64 v[36:37], v[36:37], 0, v[200:201]
	global_store_dwordx4 v[36:37], v[32:35], off
	s_nop 1
	v_fmamk_f32 v32, v139, 0x3a000000, v145
	v_rsq_f32_e32 v32, v32
	s_nop 0
	v_pk_mul_f32 v[28:29], v[28:29], v[32:33] op_sel_hi:[1,0]
	v_pk_mul_f32 v[34:35], v[18:19], v[32:33] op_sel_hi:[1,0]
	v_pk_mul_f32 v[18:19], v[16:17], v[32:33] op_sel_hi:[1,0]
	v_pk_mul_f32 v[20:21], v[20:21], v[32:33] op_sel_hi:[1,0]
	v_pk_mul_f32 v[30:31], v[30:31], v[32:33] op_sel_hi:[1,0]
	v_pk_mul_f32 v[22:23], v[22:23], v[32:33] op_sel_hi:[1,0]
	v_pk_mul_f32 v[24:25], v[24:25], v[32:33] op_sel_hi:[1,0]
	v_pk_mul_f32 v[26:27], v[26:27], v[32:33] op_sel_hi:[1,0]
	v_pk_mul_f32 v[154:155], v[28:29], s[100:101]
; __device__ __forceinline__ unsigned cvt_pk_bf16(float lo, float hi) { unsigned r; asm volatile("v_cvt_pk_bf16_f32 %0, %1, %2" : "=v"(r) : "v"(lo), "v"(hi)); return r; }
; __device__ __forceinline__ float silu_mul(float g, float u) { return g * __builtin_amdgcn_rcpf(1.0f + __builtin_amdgcn_exp2f(-1.4426950408889634f * g)) * u; }
;     __device__ __forceinline__ void operator()(const f32x4 (&acc)[2][2][4][2], const Unit& u, int wr, int wc, int fr, int fq) const {
;     ...
;             for (int m = 0; m < 4; ++m) {
;                 const int row = row0 + ai * HALF + m * 16;
;                 const float r = __builtin_amdgcn_rsqf(rs[ai][m] * (1.0f / DM) + EPSN);
;                 const f32x4 g0 = acc[ai][0][m][0] * r, g1 = acc[ai][0][m][1] * r, u0 = acc[ai][1][m][0] * r, u1 = acc[ai][1][m][1] * r;
;                 u32x4 w;
;                 w.x = cvt_pk_bf16(silu_mul(g0[0], u0[0]), silu_mul(g0[1], u0[1])); w.y = cvt_pk_bf16(silu_mul(g0[2], u0[2]), silu_mul(g0[3], u0[3]));
;                 w.z = cvt_pk_bf16(silu_mul(g1[0], u1[0]), silu_mul(g1[1], u1[1])); w.w = cvt_pk_bf16(silu_mul(g1[2], u1[2]), silu_mul(g1[3], u1[3]));
;                 *(u32x4*)(act + (((size_t)u.pm * (DFF / 64) + (u.pn * 2 + (wc >> 1))) * 256 + (row - u.pm * BM)) * 64 + (wc & 1) * 32 + 8 * fq) = w;
	v_pk_mul_f32 v[156:157], v[30:31], s[100:101]
	v_exp_f32_e32 v154, v154
	v_exp_f32_e32 v155, v155
	v_exp_f32_e32 v156, v156
	v_exp_f32_e32 v157, v157
	v_pk_add_f32 v[154:155], v[154:155], 1.0 op_sel_hi:[1,0]
	v_pk_add_f32 v[156:157], v[156:157], 1.0 op_sel_hi:[1,0]
	v_rcp_f32_e32 v154, v154
	v_rcp_f32_e32 v155, v155
	v_rcp_f32_e32 v156, v156
	v_rcp_f32_e32 v157, v157
	v_pk_mul_f32 v[154:155], v[28:29], v[154:155]
	v_pk_mul_f32 v[156:157], v[30:31], v[156:157]
	v_pk_mul_f32 v[154:155], v[20:21], v[154:155]
	v_pk_mul_f32 v[156:157], v[22:23], v[156:157]
	v_pk_mul_f32 v[158:159], v[24:25], s[100:101]
	v_pk_mul_f32 v[160:161], v[26:27], s[100:101]
	v_exp_f32_e32 v158, v158
	v_exp_f32_e32 v159, v159
	v_exp_f32_e32 v160, v160
	v_exp_f32_e32 v161, v161
	v_pk_add_f32 v[158:159], v[158:159], 1.0 op_sel_hi:[1,0]
	v_pk_add_f32 v[160:161], v[160:161], 1.0 op_sel_hi:[1,0]
	v_rcp_f32_e32 v158, v158
	v_rcp_f32_e32 v159, v159
	v_rcp_f32_e32 v160, v160
	v_rcp_f32_e32 v161, v161
	v_pk_mul_f32 v[158:159], v[24:25], v[158:159]
	v_pk_mul_f32 v[160:161], v[26:27], v[160:161]
	v_pk_mul_f32 v[158:159], v[18:19], v[158:159]
	v_pk_mul_f32 v[160:161], v[34:35], v[160:161]
	v_cvt_pk_bf16_f32 v16, v154, v155
	v_cvt_pk_bf16_f32 v17, v156, v157
	v_cvt_pk_bf16_f32 v18, v158, v159
	v_cvt_pk_bf16_f32 v19, v160, v161
	v_mov_b32_e32 v21, v201
	s_nop 0
	s_nop 0
	s_nop 0
	s_nop 0
	v_add_u32_e32 v20, 0xa0, v128
	v_lshlrev_b64 v[20:21], 7, v[20:21]
	v_lshl_add_u64 v[20:21], s[38:39], 0, v[20:21]
	v_lshl_add_u64 v[20:21], v[20:21], 0, s[22:23]
	v_lshl_add_u64 v[20:21], v[20:21], 0, v[200:201]
	global_store_dwordx4 v[20:21], v[16:19], off
	s_nop 1
	v_fmamk_f32 v16, v137, 0x3a000000, v145
	v_rsq_f32_e32 v16, v16
	s_nop 0
	v_pk_mul_f32 v[12:13], v[12:13], v[16:17] op_sel_hi:[1,0]
	v_pk_mul_f32 v[18:19], v[2:3], v[16:17] op_sel_hi:[1,0]
	v_pk_mul_f32 v[2:3], v[0:1], v[16:17] op_sel_hi:[1,0]
	v_pk_mul_f32 v[4:5], v[4:5], v[16:17] op_sel_hi:[1,0]
	v_pk_mul_f32 v[14:15], v[14:15], v[16:17] op_sel_hi:[1,0]
	v_pk_mul_f32 v[6:7], v[6:7], v[16:17] op_sel_hi:[1,0]
	v_pk_mul_f32 v[8:9], v[8:9], v[16:17] op_sel_hi:[1,0]
	v_pk_mul_f32 v[10:11], v[10:11], v[16:17] op_sel_hi:[1,0]
	v_pk_mul_f32 v[154:155], v[12:13], s[100:101]
	v_pk_mul_f32 v[156:157], v[14:15], s[100:101]
	v_exp_f32_e32 v154, v154
	v_exp_f32_e32 v155, v155
	v_exp_f32_e32 v156, v156
	v_exp_f32_e32 v157, v157
	v_pk_add_f32 v[154:155], v[154:155], 1.0 op_sel_hi:[1,0]
	v_pk_add_f32 v[156:157], v[156:157], 1.0 op_sel_hi:[1,0]
	v_rcp_f32_e32 v154, v154
	v_rcp_f32_e32 v155, v155
	v_rcp_f32_e32 v156, v156
	v_rcp_f32_e32 v157, v157
	v_pk_mul_f32 v[154:155], v[12:13], v[154:155]
	v_pk_mul_f32 v[156:157], v[14:15], v[156:157]
	v_pk_mul_f32 v[154:155], v[4:5], v[154:155]
	v_pk_mul_f32 v[156:157], v[6:7], v[156:157]
	v_pk_mul_f32 v[158:159], v[8:9], s[100:101]
	v_pk_mul_f32 v[160:161], v[10:11], s[100:101]
	v_exp_f32_e32 v158, v158
	v_exp_f32_e32 v159, v159
	v_exp_f32_e32 v160, v160
	v_exp_f32_e32 v161, v161
	v_pk_add_f32 v[158:159], v[158:159], 1.0 op_sel_hi:[1,0]
	v_pk_add_f32 v[160:161], v[160:161], 1.0 op_sel_hi:[1,0]
	v_rcp_f32_e32 v158, v158
	v_rcp_f32_e32 v159, v159
	v_rcp_f32_e32 v160, v160
	v_rcp_f32_e32 v161, v161
	v_pk_mul_f32 v[158:159], v[8:9], v[158:159]
	v_pk_mul_f32 v[160:161], v[10:11], v[160:161]
	v_pk_mul_f32 v[158:159], v[2:3], v[158:159]
	v_pk_mul_f32 v[160:161], v[18:19], v[160:161]
	v_cvt_pk_bf16_f32 v0, v154, v155
	v_cvt_pk_bf16_f32 v1, v156, v157
	v_cvt_pk_bf16_f32 v2, v158, v159
	v_cvt_pk_bf16_f32 v3, v160, v161
	v_mov_b32_e32 v5, v201
	s_nop 0
	s_nop 0
	s_nop 0
	s_nop 0
	v_add_u32_e32 v4, 0xb0, v128
	v_lshlrev_b64 v[4:5], 7, v[4:5]
	v_lshl_add_u64 v[4:5], s[38:39], 0, v[4:5]
	v_lshl_add_u64 v[4:5], v[4:5], 0, s[22:23]
	v_lshl_add_u64 v[4:5], v[4:5], 0, v[200:201]
	global_store_dwordx4 v[4:5], v[0:3], off
	s_andn2_b64 vcc, exec, s[30:31]
	s_mov_b64 s[30:31], -1
	s_cbranch_vccnz .LBB0_269
	s_andn2_b64 vcc, exec, s[0:1]
	s_cbranch_vccnz .LBB0_268
	s_barrier
	s_branch .LBB0_268

; #define PG8_STAGE(bufoff, gbase, voff) do { _Pragma("unroll") for (int _i = 0; _i < 2; ++_i) \
;         __builtin_amdgcn_global_load_lds((const unsigned*)((const char*)(gbase) + (voff)[_i]), (PG8_LAS unsigned*)(lds + (bufoff) + ldsw + _i * 8192), 16, 0, 0); } while (0)
; #define PG8_LDA(dst, b, h) do { _Pragma("unroll") for (int m = 0; m < 4; ++m) _Pragma("unroll") for (int k = 0; k < 2; ++k) dst[m][k] = *(const PG8_LAS bf16x8*)(lds + PG8_SA(b, h) + aoff + m * 2048 + k * 1024); } while (0)
; #define PG8_LDB(dst, b, h) do { _Pragma("unroll") for (int n = 0; n < 2; ++n) _Pragma("unroll") for (int k = 0; k < 2; ++k) dst[n][k] = *(const PG8_LAS bf16x8*)(lds + PG8_SB(b, h) + boff + n * 2048 + k * 1024); } while (0)
; #define PG8_WAIT_V(n) asm volatile("s_waitcnt vmcnt(" #n ")" ::: "memory")
; #define PG8_WAIT_L(n) asm volatile("s_waitcnt lgkmcnt(" #n ")" ::: "memory")
; #define PG8_BAR __builtin_amdgcn_s_barrier()
; #define PG8_SCHED __builtin_amdgcn_sched_barrier(0)
;     __device__ __forceinline__ void operator()(const f32x4 (&acc)[2][2][4][2], const Unit& u, int wr, int wc, int fr, int fq) const {
;     ...
;             for (int m = 0; m < 4; ++m) rs[ai][m] = ss[row0 + ai * HALF + m * 16];
; template <class Epi, class Sched, bool ALIGN_EPI = false, bool SP2 = false>
; __device__ __forceinline__ void gemm_phase(PG8_LAS unsigned char* lds, const Gemm g, const Sched& S, const Epi& E) {
;     ...
;         const bool has_next = S.next(ui + 1, nxt);
;         const char* nA = has_next ? (const char*)g.A + (size_t)nxt.pm * tstep + (size_t)nxt.k0 * kstepA : cA; const char* nB = has_next ? (const char*)g.Bt + (size_t)nxt.pn * tstep + (size_t)nxt.k0 * kstepB : cB;
;         for (int t = 0; t < nt; t += 2) {
;             const bool last = (t == nt - 2);
;             const char* a1 = cA + (size_t)(t + 1) * kstepA;
;             const char* a2 = last ? nA : cA + (size_t)(t + 2) * kstepA; const char* b2 = last ? nB : cB + (size_t)(t + 2) * kstepB;
;             const char* a3 = a2 + kstepA; const char* b3 = b2 + kstepB;
;             if (last && has_next) S.a_ready(nxt);
;             if constexpr (SP2) {
;             PG8_LDB(B0, 0, 0); PG8_LDB(B1, 0, 1); PG8_SCHED; PG8_LDA(At, 0, 0); PG8_STAGE(PG8_SA(1, 1), a1 + hstepA, voffA);
;             PG8_WAIT_V(8); PG8_WAIT_L(0); PG8_BAR; PG8_MMA(0, 0, At, B0); PG8_MMA(0, 1, At, B1); PG8_BAR; PG8_SCHED;
.Lhf4:
	s_ashr_i32 s27, s26, 31
	s_lshl_b64 s[30:31], s[26:27], 20
	s_add_u32 s30, s96, s30
	s_addc_u32 s31, s97, s31
	s_and_b64 s[34:35], s[28:29], exec
	s_cselect_b32 s1, s31, s41
	s_cselect_b32 s27, s30, s40
	s_ashr_i32 s25, s24, 31
	s_lshl_b64 s[34:35], s[24:25], 20
	s_add_u32 s34, s10, s34
	s_addc_u32 s35, s12, s35
	s_and_b64 s[42:43], s[28:29], exec
	s_cselect_b32 s25, s35, s39
	s_cselect_b32 s37, s34, s38
	s_add_u32 s53, s38, 0x10000
	s_addc_u32 s54, s39, 0
	s_add_u32 s38, s40, 0x80080
	s_addc_u32 s39, s41, 0
	s_mov_b32 s55, -2
	v_lshlrev_b32_e32 v132, 2, v202
	s_lshl_b32 s100, s36, 10
	s_lshr_b32 s98, s13, 12
	s_lshl_b32 s98, s98, 8
	s_add_u32 s100, s100, s98
	s_add_u32 s100, s16, s100
	s_addc_u32 s101, s17, 0
	s_lshr_b32 s98, s13, 1
	s_add_i32 s98, s98, 0x20000
	s_mov_b32 m0, s98
	s_nop 0
	global_load_lds_dword v132, s[100:101]
	s_add_u32 s100, s100, 0x200
	s_addc_u32 s101, s101, 0
	s_add_i32 m0, s98, 0x100
	s_nop 0
	global_load_lds_dword v132, s[100:101]
	s_sub_u32 s100, s38, 0x80000
	s_subb_u32 s101, s39, 0
	ds_read_b128 v[132:135], v147
	ds_read_b128 v[136:139], v147 offset:1024
	ds_read_b128 v[140:143], v147 offset:2048
	ds_read_b128 v[152:155], v147 offset:3072
	ds_read_b128 v[156:159], v148
	ds_read_b128 v[160:163], v148 offset:1024
	ds_read_b128 v[164:167], v148 offset:2048
	ds_read_b128 v[168:171], v148 offset:3072
	s_add_u32 s40, s38, 0xfff80080
	s_addc_u32 s41, s39, -1
	s_cmp_eq_u32 s55, 28
	s_cselect_b32 s43, s1, s41
	s_cselect_b32 s42, s27, s40
	s_cselect_b32 s41, s25, s54
	s_cselect_b32 s40, s37, s53
	ds_read_b128 v[172:175], v149
	ds_read_b128 v[176:179], v149 offset:1024
	ds_read_b128 v[180:183], v149 offset:2048
	ds_read_b128 v[204:207], v149 offset:3072
	ds_read_b128 v[208:211], v149 offset:4096
	ds_read_b128 v[212:215], v149 offset:5120
	ds_read_b128 v[216:219], v149 offset:6144
	ds_read_b128 v[220:223], v149 offset:7168
	s_mov_b32 m0, s48
	s_nop 0
	global_load_lds_dwordx4 v128, s[100:101]
	s_mov_b32 m0, s49
	s_nop 0
	global_load_lds_dwordx4 v130, s[100:101]
	s_add_i32 m0, s13, 0xc000
	s_nop 0
	global_load_lds_dwordx4 v128, s[38:39]
	s_add_i32 m0, s13, 0xe000
	s_nop 0
	global_load_lds_dwordx4 v130, s[38:39]
	s_waitcnt vmcnt(8)
	s_waitcnt lgkmcnt(0)
	s_setprio 1
	s_barrier
	v_mfma_f32_16x16x32_bf16 v[124:127], v[132:135], v[172:175], 0
	v_mfma_f32_16x16x32_bf16 v[120:123], v[140:143], v[172:175], 0
	v_mfma_f32_16x16x32_bf16 v[108:111], v[132:135], v[180:183], 0
	v_mfma_f32_16x16x32_bf16 v[104:107], v[140:143], v[180:183], 0
	v_mfma_f32_16x16x32_bf16 v[92:95], v[132:135], v[208:211], 0
	v_mfma_f32_16x16x32_bf16 v[88:91], v[140:143], v[208:211], 0
	v_mfma_f32_16x16x32_bf16 v[76:79], v[132:135], v[216:219], 0
	v_mfma_f32_16x16x32_bf16 v[72:75], v[140:143], v[216:219], 0
	v_mfma_f32_16x16x32_bf16 v[124:127], v[136:139], v[176:179], v[124:127]
	v_mfma_f32_16x16x32_bf16 v[120:123], v[152:155], v[176:179], v[120:123]
	v_mfma_f32_16x16x32_bf16 v[108:111], v[136:139], v[204:207], v[108:111]
	v_mfma_f32_16x16x32_bf16 v[104:107], v[152:155], v[204:207], v[104:107]
	v_mfma_f32_16x16x32_bf16 v[92:95], v[136:139], v[212:215], v[92:95]
	v_mfma_f32_16x16x32_bf16 v[88:91], v[152:155], v[212:215], v[88:91]
	v_mfma_f32_16x16x32_bf16 v[76:79], v[136:139], v[220:223], v[76:79]
	v_mfma_f32_16x16x32_bf16 v[72:75], v[152:155], v[220:223], v[72:75]
	v_mfma_f32_16x16x32_bf16 v[116:119], v[156:159], v[172:175], 0
	v_mfma_f32_16x16x32_bf16 v[112:115], v[164:167], v[172:175], 0
	v_mfma_f32_16x16x32_bf16 v[100:103], v[156:159], v[180:183], 0
	v_mfma_f32_16x16x32_bf16 v[96:99], v[164:167], v[180:183], 0
	v_mfma_f32_16x16x32_bf16 v[84:87], v[156:159], v[208:211], 0
	v_mfma_f32_16x16x32_bf16 v[80:83], v[164:167], v[208:211], 0
	v_mfma_f32_16x16x32_bf16 v[68:71], v[156:159], v[216:219], 0
	v_mfma_f32_16x16x32_bf16 v[64:67], v[164:167], v[216:219], 0
	v_mfma_f32_16x16x32_bf16 v[116:119], v[160:163], v[176:179], v[116:119]
	v_mfma_f32_16x16x32_bf16 v[112:115], v[168:171], v[176:179], v[112:115]
	v_mfma_f32_16x16x32_bf16 v[100:103], v[160:163], v[204:207], v[100:103]
	v_mfma_f32_16x16x32_bf16 v[96:99], v[168:171], v[204:207], v[96:99]
	v_mfma_f32_16x16x32_bf16 v[84:87], v[160:163], v[212:215], v[84:87]
	v_mfma_f32_16x16x32_bf16 v[80:83], v[168:171], v[212:215], v[80:83]
	v_mfma_f32_16x16x32_bf16 v[68:71], v[160:163], v[220:223], v[68:71]
	v_mfma_f32_16x16x32_bf16 v[64:67], v[168:171], v[220:223], v[64:67]
	s_barrier
	s_setprio 0
	s_add_i32 s56, s50, s2
	s_mov_b32 m0, s56
	ds_read_b128 v[172:175], v149 offset:16384
	ds_read_b128 v[176:179], v149 offset:17408
	ds_read_b128 v[180:183], v149 offset:18432
	ds_read_b128 v[204:207], v149 offset:19456
	ds_read_b128 v[208:211], v149 offset:20480
	ds_read_b128 v[212:215], v149 offset:21504
	ds_read_b128 v[216:219], v149 offset:22528
	ds_read_b128 v[220:223], v149 offset:23552
	global_load_lds_dwordx4 v194, s[40:41]
	s_add_i32 m0, s56, 0x2000
	s_add_u32 s56, s40, 0x4000
	s_addc_u32 s57, s41, 0
	s_add_i32 s58, s51, s2
	global_load_lds_dwordx4 v198, s[40:41]
	s_mov_b32 m0, s58
	s_nop 0
	global_load_lds_dwordx4 v194, s[56:57]
	s_add_i32 m0, s58, 0x2000
	s_nop 0
	global_load_lds_dwordx4 v198, s[56:57]
	s_waitcnt vmcnt(6)
	s_waitcnt lgkmcnt(0)
	s_setprio 1
	s_barrier
; #define PG8_STAGE(bufoff, gbase, voff) do { _Pragma("unroll") for (int _i = 0; _i < 2; ++_i) \
;         __builtin_amdgcn_global_load_lds((const unsigned*)((const char*)(gbase) + (voff)[_i]), (PG8_LAS unsigned*)(lds + (bufoff) + ldsw + _i * 8192), 16, 0, 0); } while (0)
; #define PG8_LDA(dst, b, h) do { _Pragma("unroll") for (int m = 0; m < 4; ++m) _Pragma("unroll") for (int k = 0; k < 2; ++k) dst[m][k] = *(const PG8_LAS bf16x8*)(lds + PG8_SA(b, h) + aoff + m * 2048 + k * 1024); } while (0)
; #define PG8_LDB(dst, b, h) do { _Pragma("unroll") for (int n = 0; n < 2; ++n) _Pragma("unroll") for (int k = 0; k < 2; ++k) dst[n][k] = *(const PG8_LAS bf16x8*)(lds + PG8_SB(b, h) + boff + n * 2048 + k * 1024); } while (0)
; #define PG8_MMA(ai, bj, At, Bt) do { __builtin_amdgcn_s_setprio(1); _Pragma("unroll") for (int m = 0; m < 4; ++m) _Pragma("unroll") for (int n = 0; n < 2; ++n) _Pragma("unroll") for (int k = 0; k < 2; ++k) \
;         acc[ai][bj][m][n] = __builtin_amdgcn_mfma_f32_16x16x32_bf16(Bt[n][k], At[m][k], acc[ai][bj][m][n], 0, 0, 0); __builtin_amdgcn_s_setprio(0); } while (0)
; #define PG8_WAIT_V(n) asm volatile("s_waitcnt vmcnt(" #n ")" ::: "memory")
; #define PG8_WAIT_L(n) asm volatile("s_waitcnt lgkmcnt(" #n ")" ::: "memory")
; #define PG8_BAR __builtin_amdgcn_s_barrier()
; #define PG8_SCHED __builtin_amdgcn_sched_barrier(0)
; template <class Epi, class Sched, bool ALIGN_EPI = false, bool SP2 = false>
; __device__ __forceinline__ void gemm_phase(PG8_LAS unsigned char* lds, const Gemm g, const Sched& S, const Epi& E) {
;     ...
;             PG8_WAIT_V(8); PG8_WAIT_L(0); PG8_BAR; PG8_MMA(0, 0, At, B0); PG8_MMA(0, 1, At, B1); PG8_BAR; PG8_SCHED;
;             PG8_LDA(At, 0, 1); PG8_STAGE(PG8_SB(0, 0), b2, voffB); PG8_STAGE(PG8_SB(0, 1), b2 + hstepB, voffB); PG8_STAGE(PG8_SA(0, 0), a2, voffA);
;             PG8_WAIT_V(8); PG8_WAIT_L(0); PG8_BAR; PG8_MMA(1, 0, At, B0); PG8_MMA(1, 1, At, B1); PG8_BAR; PG8_SCHED;
;             PG8_LDB(B0, 1, 0); PG8_LDB(B1, 1, 1); PG8_SCHED; PG8_LDA(At, 1, 0); PG8_STAGE(PG8_SA(0, 1), a2 + hstepA, voffA);
;             PG8_WAIT_V(8); PG8_WAIT_L(0); PG8_BAR; PG8_MMA(0, 0, At, B0); PG8_MMA(0, 1, At, B1); PG8_BAR; PG8_SCHED;
	v_mfma_f32_16x16x32_bf16 v[60:63], v[132:135], v[172:175], 0
	v_mfma_f32_16x16x32_bf16 v[56:59], v[140:143], v[172:175], 0
	v_mfma_f32_16x16x32_bf16 v[44:47], v[132:135], v[180:183], 0
	v_mfma_f32_16x16x32_bf16 v[40:43], v[140:143], v[180:183], 0
	v_mfma_f32_16x16x32_bf16 v[28:31], v[132:135], v[208:211], 0
	v_mfma_f32_16x16x32_bf16 v[24:27], v[140:143], v[208:211], 0
	v_mfma_f32_16x16x32_bf16 v[12:15], v[132:135], v[216:219], 0
	v_mfma_f32_16x16x32_bf16 v[8:11], v[140:143], v[216:219], 0
	v_mfma_f32_16x16x32_bf16 v[60:63], v[136:139], v[176:179], v[60:63]
	v_mfma_f32_16x16x32_bf16 v[56:59], v[152:155], v[176:179], v[56:59]
	v_mfma_f32_16x16x32_bf16 v[44:47], v[136:139], v[204:207], v[44:47]
	v_mfma_f32_16x16x32_bf16 v[40:43], v[152:155], v[204:207], v[40:43]
	v_mfma_f32_16x16x32_bf16 v[28:31], v[136:139], v[212:215], v[28:31]
	v_mfma_f32_16x16x32_bf16 v[24:27], v[152:155], v[212:215], v[24:27]
	v_mfma_f32_16x16x32_bf16 v[12:15], v[136:139], v[220:223], v[12:15]
	v_mfma_f32_16x16x32_bf16 v[8:11], v[152:155], v[220:223], v[8:11]
	v_mfma_f32_16x16x32_bf16 v[52:55], v[156:159], v[172:175], 0
	v_mfma_f32_16x16x32_bf16 v[48:51], v[164:167], v[172:175], 0
	v_mfma_f32_16x16x32_bf16 v[36:39], v[156:159], v[180:183], 0
	v_mfma_f32_16x16x32_bf16 v[32:35], v[164:167], v[180:183], 0
	v_mfma_f32_16x16x32_bf16 v[20:23], v[156:159], v[208:211], 0
	v_mfma_f32_16x16x32_bf16 v[16:19], v[164:167], v[208:211], 0
	v_mfma_f32_16x16x32_bf16 v[4:7], v[156:159], v[216:219], 0
	v_mfma_f32_16x16x32_bf16 v[0:3], v[164:167], v[216:219], 0
	v_mfma_f32_16x16x32_bf16 v[52:55], v[160:163], v[176:179], v[52:55]
	v_mfma_f32_16x16x32_bf16 v[48:51], v[168:171], v[176:179], v[48:51]
	v_mfma_f32_16x16x32_bf16 v[36:39], v[160:163], v[204:207], v[36:39]
	v_mfma_f32_16x16x32_bf16 v[32:35], v[168:171], v[204:207], v[32:35]
	v_mfma_f32_16x16x32_bf16 v[20:23], v[160:163], v[212:215], v[20:23]
	v_mfma_f32_16x16x32_bf16 v[16:19], v[168:171], v[212:215], v[16:19]
	v_mfma_f32_16x16x32_bf16 v[4:7], v[160:163], v[220:223], v[4:7]
	v_mfma_f32_16x16x32_bf16 v[0:3], v[168:171], v[220:223], v[0:3]
	s_barrier
	s_setprio 0
	s_add_i32 s56, 0, 0x18000
	v_add_u32_e32 v151, s56, v145
	s_add_i32 s57, 0, 0x1c000
	ds_read_b128 v[132:135], v151
	ds_read_b128 v[136:139], v151 offset:1024
	ds_read_b128 v[140:143], v151 offset:2048
	ds_read_b128 v[152:155], v151 offset:3072
	v_add_u32_e32 v151, s57, v145
	ds_read_b128 v[156:159], v151
	ds_read_b128 v[160:163], v151 offset:1024
	ds_read_b128 v[164:167], v151 offset:2048
	ds_read_b128 v[168:171], v151 offset:3072
	s_mov_b32 m0, s13
	s_nop 0
	global_load_lds_dwordx4 v192, s[42:43]
	s_mov_b32 m0, s14
	s_nop 0
	global_load_lds_dwordx4 v196, s[42:43]
	s_add_u32 s42, s42, 0x80000
	s_addc_u32 s43, s43, 0
	s_mov_b32 m0, s15
	ds_read_b128 v[172:175], v149 offset:32768
	ds_read_b128 v[176:179], v149 offset:33792
	ds_read_b128 v[180:183], v149 offset:34816
	ds_read_b128 v[204:207], v149 offset:35840
	ds_read_b128 v[208:211], v149 offset:36864
	ds_read_b128 v[212:215], v149 offset:37888
	ds_read_b128 v[216:219], v149 offset:38912
	ds_read_b128 v[220:223], v149 offset:39936
	global_load_lds_dwordx4 v192, s[42:43]
	s_mov_b32 m0, s44
	s_nop 0
	global_load_lds_dwordx4 v196, s[42:43]
	s_waitcnt vmcnt(8)
	s_waitcnt lgkmcnt(0)
	s_setprio 1
	s_barrier
; #define PG8_STAGE(bufoff, gbase, voff) do { _Pragma("unroll") for (int _i = 0; _i < 2; ++_i) \
;         __builtin_amdgcn_global_load_lds((const unsigned*)((const char*)(gbase) + (voff)[_i]), (PG8_LAS unsigned*)(lds + (bufoff) + ldsw + _i * 8192), 16, 0, 0); } while (0)
; #define PG8_LDA(dst, b, h) do { _Pragma("unroll") for (int m = 0; m < 4; ++m) _Pragma("unroll") for (int k = 0; k < 2; ++k) dst[m][k] = *(const PG8_LAS bf16x8*)(lds + PG8_SA(b, h) + aoff + m * 2048 + k * 1024); } while (0)
; #define PG8_LDB(dst, b, h) do { _Pragma("unroll") for (int n = 0; n < 2; ++n) _Pragma("unroll") for (int k = 0; k < 2; ++k) dst[n][k] = *(const PG8_LAS bf16x8*)(lds + PG8_SB(b, h) + boff + n * 2048 + k * 1024); } while (0)
; #define PG8_MMA(ai, bj, At, Bt) do { __builtin_amdgcn_s_setprio(1); _Pragma("unroll") for (int m = 0; m < 4; ++m) _Pragma("unroll") for (int n = 0; n < 2; ++n) _Pragma("unroll") for (int k = 0; k < 2; ++k) \
;         acc[ai][bj][m][n] = __builtin_amdgcn_mfma_f32_16x16x32_bf16(Bt[n][k], At[m][k], acc[ai][bj][m][n], 0, 0, 0); __builtin_amdgcn_s_setprio(0); } while (0)
; #define PG8_WAIT_V(n) asm volatile("s_waitcnt vmcnt(" #n ")" ::: "memory")
; #define PG8_WAIT_L(n) asm volatile("s_waitcnt lgkmcnt(" #n ")" ::: "memory")
; #define PG8_BAR __builtin_amdgcn_s_barrier()
; #define PG8_SCHED __builtin_amdgcn_sched_barrier(0)
; template <class Epi, class Sched, bool ALIGN_EPI = false, bool SP2 = false>
; __device__ __forceinline__ void gemm_phase(PG8_LAS unsigned char* lds, const Gemm g, const Sched& S, const Epi& E) {
;     ...
;             PG8_WAIT_V(8); PG8_WAIT_L(0); PG8_BAR; PG8_MMA(1, 0, At, B0); PG8_MMA(1, 1, At, B1); PG8_BAR; PG8_SCHED;
;             PG8_LDB(B0, 1, 0); PG8_LDB(B1, 1, 1); PG8_SCHED; PG8_LDA(At, 1, 0); PG8_STAGE(PG8_SA(0, 1), a2 + hstepA, voffA);
;             PG8_WAIT_V(8); PG8_WAIT_L(0); PG8_BAR; PG8_MMA(0, 0, At, B0); PG8_MMA(0, 1, At, B1); PG8_BAR; PG8_SCHED;
;             PG8_LDA(At, 1, 1); PG8_STAGE(PG8_SB(1, 0), b3, voffB); PG8_STAGE(PG8_SB(1, 1), b3 + hstepB, voffB); PG8_STAGE(PG8_SA(1, 0), a3, voffA);
;             PG8_WAIT_V(8); PG8_WAIT_L(0); PG8_BAR; PG8_MMA(1, 0, At, B0); PG8_MMA(1, 1, At, B1); PG8_BAR; PG8_SCHED;
	v_mfma_f32_16x16x32_bf16 v[124:127], v[132:135], v[172:175], v[124:127]
	v_mfma_f32_16x16x32_bf16 v[120:123], v[140:143], v[172:175], v[120:123]
	v_mfma_f32_16x16x32_bf16 v[108:111], v[132:135], v[180:183], v[108:111]
	v_mfma_f32_16x16x32_bf16 v[104:107], v[140:143], v[180:183], v[104:107]
	v_mfma_f32_16x16x32_bf16 v[92:95], v[132:135], v[208:211], v[92:95]
	v_mfma_f32_16x16x32_bf16 v[88:91], v[140:143], v[208:211], v[88:91]
	v_mfma_f32_16x16x32_bf16 v[76:79], v[132:135], v[216:219], v[76:79]
	v_mfma_f32_16x16x32_bf16 v[72:75], v[140:143], v[216:219], v[72:75]
	v_mfma_f32_16x16x32_bf16 v[124:127], v[136:139], v[176:179], v[124:127]
	v_mfma_f32_16x16x32_bf16 v[120:123], v[152:155], v[176:179], v[120:123]
	v_mfma_f32_16x16x32_bf16 v[108:111], v[136:139], v[204:207], v[108:111]
	v_mfma_f32_16x16x32_bf16 v[104:107], v[152:155], v[204:207], v[104:107]
	v_mfma_f32_16x16x32_bf16 v[92:95], v[136:139], v[212:215], v[92:95]
	v_mfma_f32_16x16x32_bf16 v[88:91], v[152:155], v[212:215], v[88:91]
	v_mfma_f32_16x16x32_bf16 v[76:79], v[136:139], v[220:223], v[76:79]
	v_mfma_f32_16x16x32_bf16 v[72:75], v[152:155], v[220:223], v[72:75]
	v_mfma_f32_16x16x32_bf16 v[116:119], v[156:159], v[172:175], v[116:119]
	v_mfma_f32_16x16x32_bf16 v[112:115], v[164:167], v[172:175], v[112:115]
	v_mfma_f32_16x16x32_bf16 v[100:103], v[156:159], v[180:183], v[100:103]
	v_mfma_f32_16x16x32_bf16 v[96:99], v[164:167], v[180:183], v[96:99]
	v_mfma_f32_16x16x32_bf16 v[84:87], v[156:159], v[208:211], v[84:87]
	v_mfma_f32_16x16x32_bf16 v[80:83], v[164:167], v[208:211], v[80:83]
	v_mfma_f32_16x16x32_bf16 v[68:71], v[156:159], v[216:219], v[68:71]
	v_mfma_f32_16x16x32_bf16 v[64:67], v[164:167], v[216:219], v[64:67]
	v_mfma_f32_16x16x32_bf16 v[116:119], v[160:163], v[176:179], v[116:119]
	v_mfma_f32_16x16x32_bf16 v[112:115], v[168:171], v[176:179], v[112:115]
	v_mfma_f32_16x16x32_bf16 v[100:103], v[160:163], v[204:207], v[100:103]
	v_mfma_f32_16x16x32_bf16 v[96:99], v[168:171], v[204:207], v[96:99]
	v_mfma_f32_16x16x32_bf16 v[84:87], v[160:163], v[212:215], v[84:87]
	v_mfma_f32_16x16x32_bf16 v[80:83], v[168:171], v[212:215], v[80:83]
	v_mfma_f32_16x16x32_bf16 v[68:71], v[160:163], v[220:223], v[68:71]
	v_mfma_f32_16x16x32_bf16 v[64:67], v[168:171], v[220:223], v[64:67]
	s_barrier
	s_setprio 0
	s_add_u32 s42, s40, 0x8000
	s_addc_u32 s43, s41, 0
	s_add_i32 s56, s56, s2
	s_mov_b32 m0, s56
	ds_read_b128 v[172:175], v149 offset:49152
	ds_read_b128 v[176:179], v149 offset:50176
	ds_read_b128 v[180:183], v149 offset:51200
	ds_read_b128 v[204:207], v149 offset:52224
	ds_read_b128 v[208:211], v149 offset:53248
	ds_read_b128 v[212:215], v149 offset:54272
	ds_read_b128 v[216:219], v149 offset:55296
	ds_read_b128 v[220:223], v149 offset:56320
	global_load_lds_dwordx4 v194, s[42:43]
	s_add_i32 m0, s56, 0x2000
	s_add_u32 s40, s40, 0xc000
	s_addc_u32 s41, s41, 0
	global_load_lds_dwordx4 v198, s[42:43]
	s_add_i32 s42, s57, s2
	s_mov_b32 m0, s42
	s_nop 0
	global_load_lds_dwordx4 v194, s[40:41]
	s_add_i32 m0, s42, 0x2000
	s_nop 0
	global_load_lds_dwordx4 v198, s[40:41]
	s_waitcnt vmcnt(6)
	s_waitcnt lgkmcnt(0)
	s_setprio 1
	s_barrier
	v_mfma_f32_16x16x32_bf16 v[60:63], v[132:135], v[172:175], v[60:63]
	v_mfma_f32_16x16x32_bf16 v[56:59], v[140:143], v[172:175], v[56:59]
	v_mfma_f32_16x16x32_bf16 v[44:47], v[132:135], v[180:183], v[44:47]
	v_mfma_f32_16x16x32_bf16 v[40:43], v[140:143], v[180:183], v[40:43]
	v_mfma_f32_16x16x32_bf16 v[28:31], v[132:135], v[208:211], v[28:31]
	v_mfma_f32_16x16x32_bf16 v[24:27], v[140:143], v[208:211], v[24:27]
	v_mfma_f32_16x16x32_bf16 v[12:15], v[132:135], v[216:219], v[12:15]
	v_mfma_f32_16x16x32_bf16 v[8:11], v[140:143], v[216:219], v[8:11]
	v_mfma_f32_16x16x32_bf16 v[60:63], v[136:139], v[176:179], v[60:63]
	v_mfma_f32_16x16x32_bf16 v[56:59], v[152:155], v[176:179], v[56:59]
	v_mfma_f32_16x16x32_bf16 v[44:47], v[136:139], v[204:207], v[44:47]
	v_mfma_f32_16x16x32_bf16 v[40:43], v[152:155], v[204:207], v[40:43]
	v_mfma_f32_16x16x32_bf16 v[28:31], v[136:139], v[212:215], v[28:31]
	v_mfma_f32_16x16x32_bf16 v[24:27], v[152:155], v[212:215], v[24:27]
	v_mfma_f32_16x16x32_bf16 v[12:15], v[136:139], v[220:223], v[12:15]
	v_mfma_f32_16x16x32_bf16 v[8:11], v[152:155], v[220:223], v[8:11]
	v_mfma_f32_16x16x32_bf16 v[52:55], v[156:159], v[172:175], v[52:55]
	v_mfma_f32_16x16x32_bf16 v[48:51], v[164:167], v[172:175], v[48:51]
	v_mfma_f32_16x16x32_bf16 v[36:39], v[156:159], v[180:183], v[36:39]
	v_mfma_f32_16x16x32_bf16 v[32:35], v[164:167], v[180:183], v[32:35]
	v_mfma_f32_16x16x32_bf16 v[20:23], v[156:159], v[208:211], v[20:23]
	v_mfma_f32_16x16x32_bf16 v[16:19], v[164:167], v[208:211], v[16:19]
	v_mfma_f32_16x16x32_bf16 v[4:7], v[156:159], v[216:219], v[4:7]
	v_mfma_f32_16x16x32_bf16 v[0:3], v[164:167], v[216:219], v[0:3]
	v_mfma_f32_16x16x32_bf16 v[52:55], v[160:163], v[176:179], v[52:55]
	v_mfma_f32_16x16x32_bf16 v[48:51], v[168:171], v[176:179], v[48:51]
	v_mfma_f32_16x16x32_bf16 v[36:39], v[160:163], v[204:207], v[36:39]
	v_mfma_f32_16x16x32_bf16 v[32:35], v[168:171], v[204:207], v[32:35]
	v_mfma_f32_16x16x32_bf16 v[20:23], v[160:163], v[212:215], v[20:23]
	v_mfma_f32_16x16x32_bf16 v[16:19], v[168:171], v[212:215], v[16:19]
	v_mfma_f32_16x16x32_bf16 v[4:7], v[160:163], v[220:223], v[4:7]
	v_mfma_f32_16x16x32_bf16 v[0:3], v[168:171], v[220:223], v[0:3]
	s_barrier
	s_setprio 0
	s_add_i32 s55, s55, 2
	s_add_u32 s53, s53, 0x10000
	s_addc_u32 s54, s54, 0
	s_add_u32 s38, s38, 0x100
	s_addc_u32 s39, s39, 0
	s_cmp_gt_u32 s55, 29
	s_cbranch_scc1 .Lpeel_exit_2

; __device__ __forceinline__ float sigmoidf_(float v) { return __builtin_amdgcn_rcpf(1.0f + __builtin_amdgcn_exp2f(-1.4426950408889634f * v)); }
;     __device__ __forceinline__ void operator()(const f32x4 (&acc)[2][2][4][2], const Unit& u, int wr, int wc, int fr, int fq) const {
;         const int row0 = u.pm * BM + wr * 64 + fr, col0 = u.pn * BM + wc * 32 + 8 * fq;
;         const bool sig = (u.pn * BM >= ZO_GC);
;         float rs[2][4];
; #pragma unroll
;         for (int ai = 0; ai < 2; ++ai)
; #pragma unroll
;             for (int m = 0; m < 4; ++m) rs[ai][m] = ss[row0 + ai * HALF + m * 16];
;         __builtin_amdgcn_sched_barrier(0);
; #pragma unroll
;         for (int ai = 0; ai < 2; ++ai)
; #pragma unroll
;             for (int m = 0; m < 4; ++m) {
;                 const int row = row0 + ai * HALF + m * 16;
;                 const float r = __builtin_amdgcn_rsqf(rs[ai][m] * (1.0f / DM) + EPSN);
; #pragma unroll
;                 for (int bj = 0; bj < 2; ++bj) {
;                     f32x4 v0 = acc[ai][bj][m][0] * r, v1 = acc[ai][bj][m][1] * r;
;                     if (sig) {
; #pragma unroll
;                         for (int i = 0; i < 4; ++i) { v0[i] = sigmoidf_(v0[i]); v1[i] = sigmoidf_(v1[i]); }
.LBB0_619:
	v_and_b32_e32 v223, 15, v202
	s_lshr_b32 s98, s13, 1
	s_add_i32 s98, s98, 0x20000
	v_lshl_add_u32 v223, v223, 2, s98
	v_lshl_add_u32 v132, s36, 8, v144
	v_or_b32_e32 v138, 16, v132
	v_ashrrev_i32_e32 v133, 31, v132
	v_ashrrev_i32_e32 v139, 31, v138
	v_or_b32_e32 v136, 32, v132
	v_lshl_add_u64 v[140:141], v[132:133], 2, s[16:17]
	v_lshl_add_u64 v[134:135], v[138:139], 2, s[16:17]
	v_ashrrev_i32_e32 v137, 31, v136
	v_lshl_add_u64 v[134:135], v[136:137], 2, s[16:17]
	v_or_b32_e32 v134, 48, v132
	v_ashrrev_i32_e32 v135, 31, v134
	v_lshl_add_u64 v[142:143], v[134:135], 2, s[16:17]
	s_cmp_gt_i32 s0, 17
	s_cselect_b64 s[36:37], -1, 0
	s_cmp_lt_i32 s0, 18
	ds_read_b32 v154, v223
	ds_read_b32 v153, v223 offset:64
	ds_read_b32 v152, v223 offset:128
	ds_read_b32 v151, v223 offset:192
	ds_read_b32 v139, v223 offset:256
	ds_read_b32 v137, v223 offset:320
	ds_read_b32 v135, v223 offset:384
	ds_read_b32 v133, v223 offset:448
	s_waitcnt lgkmcnt(0)
	v_fmamk_f32 v140, v154, 0x3a000000, v150
	v_rsq_f32_e32 v140, v140
	s_nop 0
	v_pk_mul_f32 v[126:127], v[126:127], v[140:141] op_sel_hi:[1,0]
	v_pk_mul_f32 v[124:125], v[124:125], v[140:141] op_sel_hi:[1,0]
	v_pk_mul_f32 v[122:123], v[122:123], v[140:141] op_sel_hi:[1,0]
	v_pk_mul_f32 v[142:143], v[120:121], v[140:141] op_sel_hi:[1,0]
	s_cbranch_scc1 .LBB0_621
	v_mul_f32_e32 v120, 0xbfb8aa3b, v124
	v_exp_f32_e32 v120, v120
	v_mul_f32_e32 v121, 0xbfb8aa3b, v142
	v_exp_f32_e32 v121, v121
	v_mul_f32_e32 v122, 0xbfb8aa3b, v122
	v_add_f32_e32 v120, 1.0, v120
	v_rcp_f32_e32 v124, v120
	v_mul_f32_e32 v120, 0xbfb8aa3b, v125
	v_add_f32_e32 v121, 1.0, v121
	v_exp_f32_e32 v120, v120
	v_mul_f32_e32 v125, 0xbfb8aa3b, v143
	v_exp_f32_e32 v141, v125
	v_rcp_f32_e32 v142, v121
	v_mul_f32_e32 v121, 0xbfb8aa3b, v126
	v_exp_f32_e32 v121, v121
	v_exp_f32_e32 v122, v122
	v_add_f32_e32 v120, 1.0, v120
	v_rcp_f32_e32 v125, v120
	v_add_f32_e32 v120, 1.0, v141
	v_rcp_f32_e32 v143, v120
	v_add_f32_e32 v120, 1.0, v121
	v_mul_f32_e32 v121, 0xbfb8aa3b, v127
	v_rcp_f32_e32 v126, v120
	v_add_f32_e32 v120, 1.0, v122
	v_exp_f32_e32 v121, v121
	v_mul_f32_e32 v122, 0xbfb8aa3b, v123
	v_exp_f32_e32 v123, v122
	v_rcp_f32_e32 v122, v120
	v_add_f32_e32 v120, 1.0, v121
	v_rcp_f32_e32 v127, v120
	v_add_f32_e32 v120, 1.0, v123
	v_rcp_f32_e32 v123, v120

; #define PG8_STAGE(bufoff, gbase, voff) do { _Pragma("unroll") for (int _i = 0; _i < 2; ++_i) \
;         __builtin_amdgcn_global_load_lds((const unsigned*)((const char*)(gbase) + (voff)[_i]), (PG8_LAS unsigned*)(lds + (bufoff) + ldsw + _i * 8192), 16, 0, 0); } while (0)
; #define PG8_LDA(dst, b, h) do { _Pragma("unroll") for (int m = 0; m < 4; ++m) _Pragma("unroll") for (int k = 0; k < 2; ++k) dst[m][k] = *(const PG8_LAS bf16x8*)(lds + PG8_SA(b, h) + aoff + m * 2048 + k * 1024); } while (0)
; #define PG8_LDB(dst, b, h) do { _Pragma("unroll") for (int n = 0; n < 2; ++n) _Pragma("unroll") for (int k = 0; k < 2; ++k) dst[n][k] = *(const PG8_LAS bf16x8*)(lds + PG8_SB(b, h) + boff + n * 2048 + k * 1024); } while (0)
; #define PG8_WAIT_V(n) asm volatile("s_waitcnt vmcnt(" #n ")" ::: "memory")
; #define PG8_WAIT_L(n) asm volatile("s_waitcnt lgkmcnt(" #n ")" ::: "memory")
; #define PG8_BAR __builtin_amdgcn_s_barrier()
; #define PG8_SCHED __builtin_amdgcn_sched_barrier(0)
;     __device__ __forceinline__ void operator()(const f32x4 (&acc)[2][2][4][2], const Unit& u, int wr, int wc, int fr, int fq) const {
;     ...
;             for (int m = 0; m < 4; ++m) rs[ai][m] = ss[row0 + ai * HALF + m * 16];
; template <class Epi, class Sched, bool ALIGN_EPI = false, bool SP2 = false>
; __device__ __forceinline__ void gemm_phase(PG8_LAS unsigned char* lds, const Gemm g, const Sched& S, const Epi& E) {
;     ...
;         const bool has_next = S.next(ui + 1, nxt);
;         const char* nA = has_next ? (const char*)g.A + (size_t)nxt.pm * tstep + (size_t)nxt.k0 * kstepA : cA; const char* nB = has_next ? (const char*)g.Bt + (size_t)nxt.pn * tstep + (size_t)nxt.k0 * kstepB : cB;
;         for (int t = 0; t < nt; t += 2) {
;             const bool last = (t == nt - 2);
;             const char* a1 = cA + (size_t)(t + 1) * kstepA;
;             const char* a2 = last ? nA : cA + (size_t)(t + 2) * kstepA; const char* b2 = last ? nB : cB + (size_t)(t + 2) * kstepB;
;             const char* a3 = a2 + kstepA; const char* b3 = b2 + kstepB;
;             if (last && has_next) S.a_ready(nxt);
;             if constexpr (SP2) {
;             PG8_LDB(B0, 0, 0); PG8_LDB(B1, 0, 1); PG8_SCHED; PG8_LDA(At, 0, 0); PG8_STAGE(PG8_SA(1, 1), a1 + hstepA, voffA);
;             PG8_WAIT_V(8); PG8_WAIT_L(0); PG8_BAR; PG8_MMA(0, 0, At, B0); PG8_MMA(0, 1, At, B1); PG8_BAR; PG8_SCHED;
.Lhf10:
	s_ashr_i32 s23, s22, 31
	s_lshl_b64 s[26:27], s[22:23], 20
	s_add_u32 s26, s96, s26
	s_addc_u32 s27, s97, s27
	s_and_b64 s[28:29], s[24:25], exec
	s_cselect_b32 s23, s27, s37
	s_cselect_b32 s49, s26, s36
	s_ashr_i32 s21, s20, 31
	s_lshl_b64 s[28:29], s[20:21], 20
	s_add_u32 s28, s10, s28
	s_addc_u32 s29, s14, s29
	s_and_b64 s[38:39], s[24:25], exec
	s_cselect_b32 s21, s29, s35
	s_cselect_b32 s50, s28, s34
	s_add_u32 s51, s34, 0x10000
	s_addc_u32 s52, s35, 0
	s_add_u32 s34, s36, 0x80080
	s_addc_u32 s35, s37, 0
	s_mov_b32 s53, -2
	v_lshlrev_b32_e32 v136, 2, v202
	s_lshl_b32 s100, s30, 10
	s_lshr_b32 s98, s15, 12
	s_lshl_b32 s98, s98, 8
	s_add_u32 s100, s100, s98
	s_add_u32 s100, s76, s100
	s_addc_u32 s101, s77, 0
	s_lshr_b32 s98, s15, 1
	s_add_i32 s98, s98, 0x20000
	s_mov_b32 m0, s98
	s_nop 0
	global_load_lds_dword v136, s[100:101]
	s_add_u32 s100, s100, 0x200
	s_addc_u32 s101, s101, 0
	s_add_i32 m0, s98, 0x100
	s_nop 0
	global_load_lds_dword v136, s[100:101]
	s_sub_u32 s100, s34, 0x80000
	s_subb_u32 s101, s35, 0
	ds_read_b128 v[136:139], v129
	ds_read_b128 v[144:147], v129 offset:1024
	ds_read_b128 v[148:151], v129 offset:2048
	ds_read_b128 v[152:155], v129 offset:3072
	ds_read_b128 v[156:159], v141
	ds_read_b128 v[160:163], v141 offset:1024
	ds_read_b128 v[164:167], v141 offset:2048
	ds_read_b128 v[168:171], v141 offset:3072
	s_add_u32 s36, s34, 0xfff80080
	s_addc_u32 s37, s35, -1
	s_cmp_eq_u32 s53, 28
	s_cselect_b32 s39, s23, s37
	s_cselect_b32 s38, s49, s36
	s_cselect_b32 s37, s21, s52
	s_cselect_b32 s36, s50, s51
	ds_read_b128 v[172:175], v142
	ds_read_b128 v[176:179], v142 offset:1024
	ds_read_b128 v[180:183], v142 offset:2048
	ds_read_b128 v[184:187], v142 offset:3072
	ds_read_b128 v[188:191], v142 offset:4096
	ds_read_b128 v[204:207], v142 offset:5120
	ds_read_b128 v[208:211], v142 offset:6144
	ds_read_b128 v[212:215], v142 offset:7168
	s_mov_b32 m0, s43
	s_nop 0
	global_load_lds_dwordx4 v132, s[100:101]
	s_mov_b32 m0, s44
	s_nop 0
	global_load_lds_dwordx4 v134, s[100:101]
	s_add_i32 m0, s15, 0xc000
	s_nop 0
	global_load_lds_dwordx4 v132, s[34:35]
	s_add_i32 m0, s15, 0xe000
	s_nop 0
	global_load_lds_dwordx4 v134, s[34:35]
	s_waitcnt vmcnt(8)
	s_waitcnt lgkmcnt(0)
	s_setprio 1
	s_barrier
	v_mfma_f32_16x16x32_bf16 v[124:127], v[136:139], v[172:175], 0
	v_mfma_f32_16x16x32_bf16 v[120:123], v[148:151], v[172:175], 0
	v_mfma_f32_16x16x32_bf16 v[108:111], v[136:139], v[180:183], 0
	v_mfma_f32_16x16x32_bf16 v[104:107], v[148:151], v[180:183], 0
	v_mfma_f32_16x16x32_bf16 v[92:95], v[136:139], v[188:191], 0
	v_mfma_f32_16x16x32_bf16 v[88:91], v[148:151], v[188:191], 0
	v_mfma_f32_16x16x32_bf16 v[76:79], v[136:139], v[208:211], 0
	v_mfma_f32_16x16x32_bf16 v[72:75], v[148:151], v[208:211], 0
	v_mfma_f32_16x16x32_bf16 v[124:127], v[144:147], v[176:179], v[124:127]
	v_mfma_f32_16x16x32_bf16 v[120:123], v[152:155], v[176:179], v[120:123]
	v_mfma_f32_16x16x32_bf16 v[108:111], v[144:147], v[184:187], v[108:111]
	v_mfma_f32_16x16x32_bf16 v[104:107], v[152:155], v[184:187], v[104:107]
	v_mfma_f32_16x16x32_bf16 v[92:95], v[144:147], v[204:207], v[92:95]
	v_mfma_f32_16x16x32_bf16 v[88:91], v[152:155], v[204:207], v[88:91]
	v_mfma_f32_16x16x32_bf16 v[76:79], v[144:147], v[212:215], v[76:79]
	v_mfma_f32_16x16x32_bf16 v[72:75], v[152:155], v[212:215], v[72:75]
	v_mfma_f32_16x16x32_bf16 v[116:119], v[156:159], v[172:175], 0
	v_mfma_f32_16x16x32_bf16 v[112:115], v[164:167], v[172:175], 0
	v_mfma_f32_16x16x32_bf16 v[100:103], v[156:159], v[180:183], 0
	v_mfma_f32_16x16x32_bf16 v[96:99], v[164:167], v[180:183], 0
	v_mfma_f32_16x16x32_bf16 v[84:87], v[156:159], v[188:191], 0
	v_mfma_f32_16x16x32_bf16 v[80:83], v[164:167], v[188:191], 0
	v_mfma_f32_16x16x32_bf16 v[68:71], v[156:159], v[208:211], 0
	v_mfma_f32_16x16x32_bf16 v[64:67], v[164:167], v[208:211], 0
	v_mfma_f32_16x16x32_bf16 v[116:119], v[160:163], v[176:179], v[116:119]
	v_mfma_f32_16x16x32_bf16 v[112:115], v[168:171], v[176:179], v[112:115]
	v_mfma_f32_16x16x32_bf16 v[100:103], v[160:163], v[184:187], v[100:103]
	v_mfma_f32_16x16x32_bf16 v[96:99], v[168:171], v[184:187], v[96:99]
	v_mfma_f32_16x16x32_bf16 v[84:87], v[160:163], v[204:207], v[84:87]
	v_mfma_f32_16x16x32_bf16 v[80:83], v[168:171], v[204:207], v[80:83]
	v_mfma_f32_16x16x32_bf16 v[68:71], v[160:163], v[212:215], v[68:71]
	v_mfma_f32_16x16x32_bf16 v[64:67], v[168:171], v[212:215], v[64:67]
	s_barrier
	s_setprio 0
	s_add_i32 s54, s46, s2
	s_mov_b32 m0, s54
	ds_read_b128 v[172:175], v142 offset:16384
	ds_read_b128 v[176:179], v142 offset:17408
	ds_read_b128 v[180:183], v142 offset:18432
	ds_read_b128 v[184:187], v142 offset:19456
	ds_read_b128 v[188:191], v142 offset:20480
	ds_read_b128 v[204:207], v142 offset:21504
	ds_read_b128 v[208:211], v142 offset:22528
	ds_read_b128 v[212:215], v142 offset:23552
	global_load_lds_dwordx4 v194, s[36:37]
	s_add_i32 m0, s54, 0x2000
	s_add_u32 s54, s36, 0x4000
	s_addc_u32 s55, s37, 0
	s_add_i32 s56, s47, s2
	global_load_lds_dwordx4 v198, s[36:37]
	s_mov_b32 m0, s56
	s_nop 0
	global_load_lds_dwordx4 v194, s[54:55]
	s_add_i32 m0, s56, 0x2000
	s_nop 0
	global_load_lds_dwordx4 v198, s[54:55]
	s_waitcnt vmcnt(6)
	s_waitcnt lgkmcnt(0)
	s_setprio 1
	s_barrier
; #define PG8_STAGE(bufoff, gbase, voff) do { _Pragma("unroll") for (int _i = 0; _i < 2; ++_i) \
;         __builtin_amdgcn_global_load_lds((const unsigned*)((const char*)(gbase) + (voff)[_i]), (PG8_LAS unsigned*)(lds + (bufoff) + ldsw + _i * 8192), 16, 0, 0); } while (0)
; #define PG8_LDA(dst, b, h) do { _Pragma("unroll") for (int m = 0; m < 4; ++m) _Pragma("unroll") for (int k = 0; k < 2; ++k) dst[m][k] = *(const PG8_LAS bf16x8*)(lds + PG8_SA(b, h) + aoff + m * 2048 + k * 1024); } while (0)
; #define PG8_LDB(dst, b, h) do { _Pragma("unroll") for (int n = 0; n < 2; ++n) _Pragma("unroll") for (int k = 0; k < 2; ++k) dst[n][k] = *(const PG8_LAS bf16x8*)(lds + PG8_SB(b, h) + boff + n * 2048 + k * 1024); } while (0)
; #define PG8_MMA(ai, bj, At, Bt) do { __builtin_amdgcn_s_setprio(1); _Pragma("unroll") for (int m = 0; m < 4; ++m) _Pragma("unroll") for (int n = 0; n < 2; ++n) _Pragma("unroll") for (int k = 0; k < 2; ++k) \
;         acc[ai][bj][m][n] = __builtin_amdgcn_mfma_f32_16x16x32_bf16(Bt[n][k], At[m][k], acc[ai][bj][m][n], 0, 0, 0); __builtin_amdgcn_s_setprio(0); } while (0)
; #define PG8_WAIT_V(n) asm volatile("s_waitcnt vmcnt(" #n ")" ::: "memory")
; #define PG8_WAIT_L(n) asm volatile("s_waitcnt lgkmcnt(" #n ")" ::: "memory")
; #define PG8_BAR __builtin_amdgcn_s_barrier()
; #define PG8_SCHED __builtin_amdgcn_sched_barrier(0)
; template <class Epi, class Sched, bool ALIGN_EPI = false, bool SP2 = false>
; __device__ __forceinline__ void gemm_phase(PG8_LAS unsigned char* lds, const Gemm g, const Sched& S, const Epi& E) {
;     ...
;             PG8_WAIT_V(8); PG8_WAIT_L(0); PG8_BAR; PG8_MMA(0, 0, At, B0); PG8_MMA(0, 1, At, B1); PG8_BAR; PG8_SCHED;
;             PG8_LDA(At, 0, 1); PG8_STAGE(PG8_SB(0, 0), b2, voffB); PG8_STAGE(PG8_SB(0, 1), b2 + hstepB, voffB); PG8_STAGE(PG8_SA(0, 0), a2, voffA);
;             PG8_WAIT_V(8); PG8_WAIT_L(0); PG8_BAR; PG8_MMA(1, 0, At, B0); PG8_MMA(1, 1, At, B1); PG8_BAR; PG8_SCHED;
;             PG8_LDB(B0, 1, 0); PG8_LDB(B1, 1, 1); PG8_SCHED; PG8_LDA(At, 1, 0); PG8_STAGE(PG8_SA(0, 1), a2 + hstepA, voffA);
;             PG8_WAIT_V(8); PG8_WAIT_L(0); PG8_BAR; PG8_MMA(0, 0, At, B0); PG8_MMA(0, 1, At, B1); PG8_BAR; PG8_SCHED;
	v_mfma_f32_16x16x32_bf16 v[60:63], v[136:139], v[172:175], 0
	v_mfma_f32_16x16x32_bf16 v[56:59], v[148:151], v[172:175], 0
	v_mfma_f32_16x16x32_bf16 v[44:47], v[136:139], v[180:183], 0
	v_mfma_f32_16x16x32_bf16 v[40:43], v[148:151], v[180:183], 0
	v_mfma_f32_16x16x32_bf16 v[28:31], v[136:139], v[188:191], 0
	v_mfma_f32_16x16x32_bf16 v[24:27], v[148:151], v[188:191], 0
	v_mfma_f32_16x16x32_bf16 v[12:15], v[136:139], v[208:211], 0
	v_mfma_f32_16x16x32_bf16 v[8:11], v[148:151], v[208:211], 0
	v_mfma_f32_16x16x32_bf16 v[60:63], v[144:147], v[176:179], v[60:63]
	v_mfma_f32_16x16x32_bf16 v[56:59], v[152:155], v[176:179], v[56:59]
	v_mfma_f32_16x16x32_bf16 v[44:47], v[144:147], v[184:187], v[44:47]
	v_mfma_f32_16x16x32_bf16 v[40:43], v[152:155], v[184:187], v[40:43]
	v_mfma_f32_16x16x32_bf16 v[28:31], v[144:147], v[204:207], v[28:31]
	v_mfma_f32_16x16x32_bf16 v[24:27], v[152:155], v[204:207], v[24:27]
	v_mfma_f32_16x16x32_bf16 v[12:15], v[144:147], v[212:215], v[12:15]
	v_mfma_f32_16x16x32_bf16 v[8:11], v[152:155], v[212:215], v[8:11]
	v_mfma_f32_16x16x32_bf16 v[52:55], v[156:159], v[172:175], 0
	v_mfma_f32_16x16x32_bf16 v[48:51], v[164:167], v[172:175], 0
	v_mfma_f32_16x16x32_bf16 v[36:39], v[156:159], v[180:183], 0
	v_mfma_f32_16x16x32_bf16 v[32:35], v[164:167], v[180:183], 0
	v_mfma_f32_16x16x32_bf16 v[20:23], v[156:159], v[188:191], 0
	v_mfma_f32_16x16x32_bf16 v[16:19], v[164:167], v[188:191], 0
	v_mfma_f32_16x16x32_bf16 v[4:7], v[156:159], v[208:211], 0
	v_mfma_f32_16x16x32_bf16 v[0:3], v[164:167], v[208:211], 0
	v_mfma_f32_16x16x32_bf16 v[52:55], v[160:163], v[176:179], v[52:55]
	v_mfma_f32_16x16x32_bf16 v[48:51], v[168:171], v[176:179], v[48:51]
	v_mfma_f32_16x16x32_bf16 v[36:39], v[160:163], v[184:187], v[36:39]
	v_mfma_f32_16x16x32_bf16 v[32:35], v[168:171], v[184:187], v[32:35]
	v_mfma_f32_16x16x32_bf16 v[20:23], v[160:163], v[204:207], v[20:23]
	v_mfma_f32_16x16x32_bf16 v[16:19], v[168:171], v[204:207], v[16:19]
	v_mfma_f32_16x16x32_bf16 v[4:7], v[160:163], v[212:215], v[4:7]
	v_mfma_f32_16x16x32_bf16 v[0:3], v[168:171], v[212:215], v[0:3]
	s_barrier
	s_setprio 0
	s_add_i32 s54, 0, 0x18000
	s_add_i32 s55, 0, 0x1c000
	v_add_u32_e32 v152, s54, v140
	v_add_u32_e32 v168, s55, v140
	ds_read_b128 v[136:139], v152
	ds_read_b128 v[144:147], v152 offset:1024
	ds_read_b128 v[148:151], v152 offset:2048
	ds_read_b128 v[152:155], v152 offset:3072
	ds_read_b128 v[156:159], v168
	ds_read_b128 v[160:163], v168 offset:1024
	ds_read_b128 v[164:167], v168 offset:2048
	ds_read_b128 v[168:171], v168 offset:3072
	s_mov_b32 m0, s15
	s_nop 0
	global_load_lds_dwordx4 v192, s[38:39]
	s_mov_b32 m0, s40
	s_nop 0
	global_load_lds_dwordx4 v196, s[38:39]
	s_add_u32 s38, s38, 0x80000
	s_addc_u32 s39, s39, 0
	s_mov_b32 m0, s41
	ds_read_b128 v[172:175], v142 offset:32768
	ds_read_b128 v[176:179], v142 offset:33792
	ds_read_b128 v[180:183], v142 offset:34816
	ds_read_b128 v[184:187], v142 offset:35840
	ds_read_b128 v[188:191], v142 offset:36864
	ds_read_b128 v[204:207], v142 offset:37888
	ds_read_b128 v[208:211], v142 offset:38912
	ds_read_b128 v[212:215], v142 offset:39936
	global_load_lds_dwordx4 v192, s[38:39]
	s_mov_b32 m0, s42
	s_nop 0
	global_load_lds_dwordx4 v196, s[38:39]
	s_waitcnt vmcnt(8)
	s_waitcnt lgkmcnt(0)
	s_setprio 1
	s_barrier
; #define PG8_STAGE(bufoff, gbase, voff) do { _Pragma("unroll") for (int _i = 0; _i < 2; ++_i) \
;         __builtin_amdgcn_global_load_lds((const unsigned*)((const char*)(gbase) + (voff)[_i]), (PG8_LAS unsigned*)(lds + (bufoff) + ldsw + _i * 8192), 16, 0, 0); } while (0)
; #define PG8_LDA(dst, b, h) do { _Pragma("unroll") for (int m = 0; m < 4; ++m) _Pragma("unroll") for (int k = 0; k < 2; ++k) dst[m][k] = *(const PG8_LAS bf16x8*)(lds + PG8_SA(b, h) + aoff + m * 2048 + k * 1024); } while (0)
; #define PG8_LDB(dst, b, h) do { _Pragma("unroll") for (int n = 0; n < 2; ++n) _Pragma("unroll") for (int k = 0; k < 2; ++k) dst[n][k] = *(const PG8_LAS bf16x8*)(lds + PG8_SB(b, h) + boff + n * 2048 + k * 1024); } while (0)
; #define PG8_MMA(ai, bj, At, Bt) do { __builtin_amdgcn_s_setprio(1); _Pragma("unroll") for (int m = 0; m < 4; ++m) _Pragma("unroll") for (int n = 0; n < 2; ++n) _Pragma("unroll") for (int k = 0; k < 2; ++k) \
;         acc[ai][bj][m][n] = __builtin_amdgcn_mfma_f32_16x16x32_bf16(Bt[n][k], At[m][k], acc[ai][bj][m][n], 0, 0, 0); __builtin_amdgcn_s_setprio(0); } while (0)
; #define PG8_WAIT_V(n) asm volatile("s_waitcnt vmcnt(" #n ")" ::: "memory")
; #define PG8_WAIT_L(n) asm volatile("s_waitcnt lgkmcnt(" #n ")" ::: "memory")
; #define PG8_BAR __builtin_amdgcn_s_barrier()
; #define PG8_SCHED __builtin_amdgcn_sched_barrier(0)
; template <class Epi, class Sched, bool ALIGN_EPI = false, bool SP2 = false>
; __device__ __forceinline__ void gemm_phase(PG8_LAS unsigned char* lds, const Gemm g, const Sched& S, const Epi& E) {
;     ...
;             PG8_WAIT_V(8); PG8_WAIT_L(0); PG8_BAR; PG8_MMA(1, 0, At, B0); PG8_MMA(1, 1, At, B1); PG8_BAR; PG8_SCHED;
;             PG8_LDB(B0, 1, 0); PG8_LDB(B1, 1, 1); PG8_SCHED; PG8_LDA(At, 1, 0); PG8_STAGE(PG8_SA(0, 1), a2 + hstepA, voffA);
;             PG8_WAIT_V(8); PG8_WAIT_L(0); PG8_BAR; PG8_MMA(0, 0, At, B0); PG8_MMA(0, 1, At, B1); PG8_BAR; PG8_SCHED;
;             PG8_LDA(At, 1, 1); PG8_STAGE(PG8_SB(1, 0), b3, voffB); PG8_STAGE(PG8_SB(1, 1), b3 + hstepB, voffB); PG8_STAGE(PG8_SA(1, 0), a3, voffA);
;             PG8_WAIT_V(8); PG8_WAIT_L(0); PG8_BAR; PG8_MMA(1, 0, At, B0); PG8_MMA(1, 1, At, B1); PG8_BAR; PG8_SCHED;
	v_mfma_f32_16x16x32_bf16 v[124:127], v[136:139], v[172:175], v[124:127]
	v_mfma_f32_16x16x32_bf16 v[120:123], v[148:151], v[172:175], v[120:123]
	v_mfma_f32_16x16x32_bf16 v[108:111], v[136:139], v[180:183], v[108:111]
	v_mfma_f32_16x16x32_bf16 v[104:107], v[148:151], v[180:183], v[104:107]
	v_mfma_f32_16x16x32_bf16 v[92:95], v[136:139], v[188:191], v[92:95]
	v_mfma_f32_16x16x32_bf16 v[88:91], v[148:151], v[188:191], v[88:91]
	v_mfma_f32_16x16x32_bf16 v[76:79], v[136:139], v[208:211], v[76:79]
	v_mfma_f32_16x16x32_bf16 v[72:75], v[148:151], v[208:211], v[72:75]
	v_mfma_f32_16x16x32_bf16 v[124:127], v[144:147], v[176:179], v[124:127]
	v_mfma_f32_16x16x32_bf16 v[120:123], v[152:155], v[176:179], v[120:123]
	v_mfma_f32_16x16x32_bf16 v[108:111], v[144:147], v[184:187], v[108:111]
	v_mfma_f32_16x16x32_bf16 v[104:107], v[152:155], v[184:187], v[104:107]
	v_mfma_f32_16x16x32_bf16 v[92:95], v[144:147], v[204:207], v[92:95]
	v_mfma_f32_16x16x32_bf16 v[88:91], v[152:155], v[204:207], v[88:91]
	v_mfma_f32_16x16x32_bf16 v[76:79], v[144:147], v[212:215], v[76:79]
	v_mfma_f32_16x16x32_bf16 v[72:75], v[152:155], v[212:215], v[72:75]
	v_mfma_f32_16x16x32_bf16 v[116:119], v[156:159], v[172:175], v[116:119]
	v_mfma_f32_16x16x32_bf16 v[112:115], v[164:167], v[172:175], v[112:115]
	v_mfma_f32_16x16x32_bf16 v[100:103], v[156:159], v[180:183], v[100:103]
	v_mfma_f32_16x16x32_bf16 v[96:99], v[164:167], v[180:183], v[96:99]
	v_mfma_f32_16x16x32_bf16 v[84:87], v[156:159], v[188:191], v[84:87]
	v_mfma_f32_16x16x32_bf16 v[80:83], v[164:167], v[188:191], v[80:83]
	v_mfma_f32_16x16x32_bf16 v[68:71], v[156:159], v[208:211], v[68:71]
	v_mfma_f32_16x16x32_bf16 v[64:67], v[164:167], v[208:211], v[64:67]
	v_mfma_f32_16x16x32_bf16 v[116:119], v[160:163], v[176:179], v[116:119]
	v_mfma_f32_16x16x32_bf16 v[112:115], v[168:171], v[176:179], v[112:115]
	v_mfma_f32_16x16x32_bf16 v[100:103], v[160:163], v[184:187], v[100:103]
	v_mfma_f32_16x16x32_bf16 v[96:99], v[168:171], v[184:187], v[96:99]
	v_mfma_f32_16x16x32_bf16 v[84:87], v[160:163], v[204:207], v[84:87]
	v_mfma_f32_16x16x32_bf16 v[80:83], v[168:171], v[204:207], v[80:83]
	v_mfma_f32_16x16x32_bf16 v[68:71], v[160:163], v[212:215], v[68:71]
	v_mfma_f32_16x16x32_bf16 v[64:67], v[168:171], v[212:215], v[64:67]
	s_barrier
	s_setprio 0
	s_add_u32 s38, s36, 0x8000
	s_addc_u32 s39, s37, 0
	s_add_i32 s54, s54, s2
	s_mov_b32 m0, s54
	ds_read_b128 v[172:175], v142 offset:49152
	ds_read_b128 v[176:179], v142 offset:50176
	ds_read_b128 v[180:183], v142 offset:51200
	ds_read_b128 v[184:187], v142 offset:52224
	ds_read_b128 v[188:191], v142 offset:53248
	ds_read_b128 v[204:207], v142 offset:54272
	ds_read_b128 v[208:211], v142 offset:55296
	ds_read_b128 v[212:215], v142 offset:56320
	global_load_lds_dwordx4 v194, s[38:39]
	s_add_i32 m0, s54, 0x2000
	s_add_u32 s36, s36, 0xc000
	s_addc_u32 s37, s37, 0
	global_load_lds_dwordx4 v198, s[38:39]
	s_add_i32 s38, s55, s2
	s_mov_b32 m0, s38
	s_nop 0
	global_load_lds_dwordx4 v194, s[36:37]
	s_add_i32 m0, s38, 0x2000
	s_nop 0
	global_load_lds_dwordx4 v198, s[36:37]
	s_waitcnt vmcnt(6)
	s_waitcnt lgkmcnt(0)
	s_setprio 1
	s_barrier
	v_mfma_f32_16x16x32_bf16 v[60:63], v[136:139], v[172:175], v[60:63]
	v_mfma_f32_16x16x32_bf16 v[56:59], v[148:151], v[172:175], v[56:59]
	v_mfma_f32_16x16x32_bf16 v[44:47], v[136:139], v[180:183], v[44:47]
	v_mfma_f32_16x16x32_bf16 v[40:43], v[148:151], v[180:183], v[40:43]
	v_mfma_f32_16x16x32_bf16 v[28:31], v[136:139], v[188:191], v[28:31]
	v_mfma_f32_16x16x32_bf16 v[24:27], v[148:151], v[188:191], v[24:27]
	v_mfma_f32_16x16x32_bf16 v[12:15], v[136:139], v[208:211], v[12:15]
	v_mfma_f32_16x16x32_bf16 v[8:11], v[148:151], v[208:211], v[8:11]
	v_mfma_f32_16x16x32_bf16 v[60:63], v[144:147], v[176:179], v[60:63]
	v_mfma_f32_16x16x32_bf16 v[56:59], v[152:155], v[176:179], v[56:59]
	v_mfma_f32_16x16x32_bf16 v[44:47], v[144:147], v[184:187], v[44:47]
	v_mfma_f32_16x16x32_bf16 v[40:43], v[152:155], v[184:187], v[40:43]
	v_mfma_f32_16x16x32_bf16 v[28:31], v[144:147], v[204:207], v[28:31]
	v_mfma_f32_16x16x32_bf16 v[24:27], v[152:155], v[204:207], v[24:27]
	v_mfma_f32_16x16x32_bf16 v[12:15], v[144:147], v[212:215], v[12:15]
	v_mfma_f32_16x16x32_bf16 v[8:11], v[152:155], v[212:215], v[8:11]
	v_mfma_f32_16x16x32_bf16 v[52:55], v[156:159], v[172:175], v[52:55]
	v_mfma_f32_16x16x32_bf16 v[48:51], v[164:167], v[172:175], v[48:51]
	v_mfma_f32_16x16x32_bf16 v[36:39], v[156:159], v[180:183], v[36:39]
	v_mfma_f32_16x16x32_bf16 v[32:35], v[164:167], v[180:183], v[32:35]
	v_mfma_f32_16x16x32_bf16 v[20:23], v[156:159], v[188:191], v[20:23]
	v_mfma_f32_16x16x32_bf16 v[16:19], v[164:167], v[188:191], v[16:19]
	v_mfma_f32_16x16x32_bf16 v[4:7], v[156:159], v[208:211], v[4:7]
	v_mfma_f32_16x16x32_bf16 v[0:3], v[164:167], v[208:211], v[0:3]
	v_mfma_f32_16x16x32_bf16 v[52:55], v[160:163], v[176:179], v[52:55]
	v_mfma_f32_16x16x32_bf16 v[48:51], v[168:171], v[176:179], v[48:51]
	v_mfma_f32_16x16x32_bf16 v[36:39], v[160:163], v[184:187], v[36:39]
	v_mfma_f32_16x16x32_bf16 v[32:35], v[168:171], v[184:187], v[32:35]
	v_mfma_f32_16x16x32_bf16 v[20:23], v[160:163], v[204:207], v[20:23]
	v_mfma_f32_16x16x32_bf16 v[16:19], v[168:171], v[204:207], v[16:19]
	v_mfma_f32_16x16x32_bf16 v[4:7], v[160:163], v[212:215], v[4:7]
	v_mfma_f32_16x16x32_bf16 v[0:3], v[168:171], v[212:215], v[0:3]
	s_barrier
	s_setprio 0
	s_add_i32 s53, s53, 2
	s_add_u32 s51, s51, 0x10000
	s_addc_u32 s52, s52, 0
	s_add_u32 s34, s34, 0x100
	s_addc_u32 s35, s35, 0
	s_cmp_gt_u32 s53, 29
	s_cbranch_scc1 .Lpeel_exit_5

; __device__ __forceinline__ unsigned cvt_pk_bf16(float lo, float hi) { unsigned r; asm volatile("v_cvt_pk_bf16_f32 %0, %1, %2" : "=v"(r) : "v"(lo), "v"(hi)); return r; }
; __device__ __forceinline__ float silu_mul(float g, float u) { return g * __builtin_amdgcn_rcpf(1.0f + __builtin_amdgcn_exp2f(-1.4426950408889634f * g)) * u; }
;     __device__ __forceinline__ void operator()(const f32x4 (&acc)[2][2][4][2], const Unit& u, int wr, int wc, int fr, int fq) const {
;         const int row0 = u.pm * BM + wr * 64 + fr, j0 = u.pn * HALF + wc * 32 + 8 * fq;
;         float rs[2][4];
; #pragma unroll
;         for (int ai = 0; ai < 2; ++ai)
; #pragma unroll
;             for (int m = 0; m < 4; ++m) rs[ai][m] = ss[row0 + ai * HALF + m * 16];
;         __builtin_amdgcn_sched_barrier(0);
; #pragma unroll
;         for (int ai = 0; ai < 2; ++ai)
; #pragma unroll
;             for (int m = 0; m < 4; ++m) {
;                 const int row = row0 + ai * HALF + m * 16;
;                 const float r = __builtin_amdgcn_rsqf(rs[ai][m] * (1.0f / DM) + EPSN);
;                 const f32x4 g0 = acc[ai][0][m][0] * r, g1 = acc[ai][0][m][1] * r, u0 = acc[ai][1][m][0] * r, u1 = acc[ai][1][m][1] * r;
;                 u32x4 w;
;                 w.x = cvt_pk_bf16(silu_mul(g0[0], u0[0]), silu_mul(g0[1], u0[1])); w.y = cvt_pk_bf16(silu_mul(g0[2], u0[2]), silu_mul(g0[3], u0[3]));
;                 w.z = cvt_pk_bf16(silu_mul(g1[0], u1[0]), silu_mul(g1[1], u1[1])); w.w = cvt_pk_bf16(silu_mul(g1[2], u1[2]), silu_mul(g1[3], u1[3]));
;                 *(u32x4*)(act + (((size_t)u.pm * (DFF / 64) + (u.pn * 2 + (wc >> 1))) * 256 + (row - u.pm * BM)) * 64 + (wc & 1) * 32 + 8 * fq) = w;
.LBB0_1342:
	v_and_b32_e32 v215, 15, v202
	s_lshr_b32 s98, s15, 1
	s_add_i32 s98, s98, 0x20000
	v_lshl_add_u32 v215, v215, 2, s98
	s_lshl_b32 s21, s30, 8
	v_add_u32_e32 v136, s21, v128
	v_ashrrev_i32_e32 v137, 31, v136
	v_lshl_add_u64 v[146:147], v[136:137], 2, s[76:77]
	v_or_b32_e32 v148, 16, v136
	v_or_b32_e32 v138, 32, v136
	v_or_b32_e32 v136, 48, v136
	v_ashrrev_i32_e32 v149, 31, v148
	v_ashrrev_i32_e32 v137, 31, v136
	v_lshl_add_u64 v[144:145], v[148:149], 2, s[76:77]
	v_ashrrev_i32_e32 v139, 31, v138
	v_lshl_add_u64 v[152:153], v[136:137], 2, s[76:77]
	v_lshl_add_u64 v[150:151], v[138:139], 2, s[76:77]
	s_nop 0
	s_nop 0
	s_nop 0
	s_nop 0
	ds_read_b32 v149, v215
	ds_read_b32 v145, v215 offset:64
	ds_read_b32 v154, v215 offset:128
	ds_read_b32 v152, v215 offset:192
	ds_read_b32 v153, v215 offset:256
	ds_read_b32 v144, v215 offset:320
	ds_read_b32 v139, v215 offset:384
	ds_read_b32 v137, v215 offset:448
	s_waitcnt lgkmcnt(0)
	s_mov_b32 s100, 0xbfb8aa3b
	s_mov_b32 s101, 0xbfb8aa3b
	v_fmamk_f32 v146, v149, 0x3a000000, v143
	v_rsq_f32_e32 v146, v146
	s_lshl_b32 s31, s31, 1
	s_or_b32 s31, s31, s45
	s_mul_hi_i32 s23, s30, 0x56
	v_pk_mul_f32 v[124:125], v[124:125], v[146:147] op_sel_hi:[1,0]
	v_pk_mul_f32 v[126:127], v[126:127], v[146:147] op_sel_hi:[1,0]
	v_pk_mul_f32 v[122:123], v[122:123], v[146:147] op_sel_hi:[1,0]
	v_pk_mul_f32 v[120:121], v[120:121], v[146:147] op_sel_hi:[1,0]
	v_pk_mul_f32 v[118:119], v[118:119], v[146:147] op_sel_hi:[1,0]
	v_pk_mul_f32 v[116:117], v[116:117], v[146:147] op_sel_hi:[1,0]
	s_mulk_i32 s30, 0x56
	v_pk_mul_f32 v[150:151], v[114:115], v[146:147] op_sel_hi:[1,0]
	s_ashr_i32 s34, s31, 31
	v_pk_mul_f32 v[114:115], v[112:113], v[146:147] op_sel_hi:[1,0]
	v_pk_mul_f32 v[156:157], v[124:125], s[100:101]
	v_pk_mul_f32 v[158:159], v[126:127], s[100:101]
	v_exp_f32_e32 v156, v156
	v_exp_f32_e32 v157, v157
	v_exp_f32_e32 v158, v158
	v_exp_f32_e32 v159, v159
	v_pk_add_f32 v[156:157], v[156:157], 1.0 op_sel_hi:[1,0]
	v_pk_add_f32 v[158:159], v[158:159], 1.0 op_sel_hi:[1,0]
	v_rcp_f32_e32 v156, v156
	v_rcp_f32_e32 v157, v157
	v_rcp_f32_e32 v158, v158
	v_rcp_f32_e32 v159, v159
	v_pk_mul_f32 v[156:157], v[124:125], v[156:157]
	v_pk_mul_f32 v[158:159], v[126:127], v[158:159]
	v_pk_mul_f32 v[156:157], v[116:117], v[156:157]
	v_pk_mul_f32 v[158:159], v[118:119], v[158:159]
	v_pk_mul_f32 v[160:161], v[120:121], s[100:101]
	v_pk_mul_f32 v[162:163], v[122:123], s[100:101]
	v_exp_f32_e32 v160, v160
	v_exp_f32_e32 v161, v161
	v_exp_f32_e32 v162, v162
	v_exp_f32_e32 v163, v163
	v_pk_add_f32 v[160:161], v[160:161], 1.0 op_sel_hi:[1,0]
	v_pk_add_f32 v[162:163], v[162:163], 1.0 op_sel_hi:[1,0]
	v_rcp_f32_e32 v160, v160
	v_rcp_f32_e32 v161, v161
	v_rcp_f32_e32 v162, v162
	v_rcp_f32_e32 v163, v163
	v_pk_mul_f32 v[160:161], v[120:121], v[160:161]
	v_pk_mul_f32 v[162:163], v[122:123], v[162:163]
	v_pk_mul_f32 v[160:161], v[114:115], v[160:161]
	v_pk_mul_f32 v[162:163], v[150:151], v[162:163]
	v_cvt_pk_bf16_f32 v112, v156, v157
	v_cvt_pk_bf16_f32 v113, v158, v159
	v_cvt_pk_bf16_f32 v114, v160, v161
	v_cvt_pk_bf16_f32 v115, v162, v163
	s_add_u32 s30, s30, s31
	s_addc_u32 s31, s23, s34
	s_lshl_b64 s[30:31], s[30:31], 15
	s_add_u32 s30, s4, s30
	s_addc_u32 s31, s5, s31
	v_lshl_add_u64 v[116:117], s[30:31], 0, v[130:131]
	v_lshl_add_u64 v[116:117], v[116:117], 0, s[16:17]
	v_lshl_add_u64 v[116:117], v[116:117], 0, v[200:201]
	global_store_dwordx4 v[116:117], v[112:115], off
	s_nop 1
	v_fmamk_f32 v112, v145, 0x3a000000, v143
	v_rsq_f32_e32 v112, v112
	s_nop 0
	v_pk_mul_f32 v[108:109], v[108:109], v[112:113] op_sel_hi:[1,0]
	v_pk_mul_f32 v[110:111], v[110:111], v[112:113] op_sel_hi:[1,0]
	v_pk_mul_f32 v[106:107], v[106:107], v[112:113] op_sel_hi:[1,0]
	v_pk_mul_f32 v[104:105], v[104:105], v[112:113] op_sel_hi:[1,0]
	v_pk_mul_f32 v[102:103], v[102:103], v[112:113] op_sel_hi:[1,0]
	v_pk_mul_f32 v[100:101], v[100:101], v[112:113] op_sel_hi:[1,0]
	v_pk_mul_f32 v[114:115], v[98:99], v[112:113] op_sel_hi:[1,0]
	v_pk_mul_f32 v[98:99], v[96:97], v[112:113] op_sel_hi:[1,0]
	v_pk_mul_f32 v[156:157], v[108:109], s[100:101]
	v_pk_mul_f32 v[158:159], v[110:111], s[100:101]
	v_exp_f32_e32 v156, v156
	v_exp_f32_e32 v157, v157
	v_exp_f32_e32 v158, v158
	v_exp_f32_e32 v159, v159
	v_pk_add_f32 v[156:157], v[156:157], 1.0 op_sel_hi:[1,0]
	v_pk_add_f32 v[158:159], v[158:159], 1.0 op_sel_hi:[1,0]
	v_rcp_f32_e32 v156, v156
	v_rcp_f32_e32 v157, v157
	v_rcp_f32_e32 v158, v158
	v_rcp_f32_e32 v159, v159
	v_pk_mul_f32 v[156:157], v[108:109], v[156:157]
	v_pk_mul_f32 v[158:159], v[110:111], v[158:159]
	v_pk_mul_f32 v[156:157], v[100:101], v[156:157]
	v_pk_mul_f32 v[158:159], v[102:103], v[158:159]
	v_pk_mul_f32 v[160:161], v[104:105], s[100:101]
	v_pk_mul_f32 v[162:163], v[106:107], s[100:101]
	v_exp_f32_e32 v160, v160
	v_exp_f32_e32 v161, v161
	v_exp_f32_e32 v162, v162
	v_exp_f32_e32 v163, v163
	v_pk_add_f32 v[160:161], v[160:161], 1.0 op_sel_hi:[1,0]
	v_pk_add_f32 v[162:163], v[162:163], 1.0 op_sel_hi:[1,0]
	v_rcp_f32_e32 v160, v160
	v_rcp_f32_e32 v161, v161
	v_rcp_f32_e32 v162, v162
	v_rcp_f32_e32 v163, v163
	v_pk_mul_f32 v[160:161], v[104:105], v[160:161]
	v_pk_mul_f32 v[162:163], v[106:107], v[162:163]
	v_pk_mul_f32 v[160:161], v[98:99], v[160:161]
	v_pk_mul_f32 v[162:163], v[114:115], v[162:163]
	v_cvt_pk_bf16_f32 v96, v156, v157
	v_cvt_pk_bf16_f32 v97, v158, v159
	v_cvt_pk_bf16_f32 v98, v160, v161
	v_cvt_pk_bf16_f32 v99, v162, v163
	v_subrev_u32_e32 v100, s21, v148
	v_ashrrev_i32_e32 v101, 31, v100
	v_lshlrev_b64 v[100:101], 7, v[100:101]
	v_lshl_add_u64 v[100:101], s[30:31], 0, v[100:101]
	v_lshl_add_u64 v[100:101], v[100:101], 0, s[16:17]
; __device__ __forceinline__ unsigned cvt_pk_bf16(float lo, float hi) { unsigned r; asm volatile("v_cvt_pk_bf16_f32 %0, %1, %2" : "=v"(r) : "v"(lo), "v"(hi)); return r; }
; __device__ __forceinline__ float silu_mul(float g, float u) { return g * __builtin_amdgcn_rcpf(1.0f + __builtin_amdgcn_exp2f(-1.4426950408889634f * g)) * u; }
;     __device__ __forceinline__ void operator()(const f32x4 (&acc)[2][2][4][2], const Unit& u, int wr, int wc, int fr, int fq) const {
;     ...
;             for (int m = 0; m < 4; ++m) {
;                 const int row = row0 + ai * HALF + m * 16;
;                 const float r = __builtin_amdgcn_rsqf(rs[ai][m] * (1.0f / DM) + EPSN);
;                 const f32x4 g0 = acc[ai][0][m][0] * r, g1 = acc[ai][0][m][1] * r, u0 = acc[ai][1][m][0] * r, u1 = acc[ai][1][m][1] * r;
;                 u32x4 w;
;                 w.x = cvt_pk_bf16(silu_mul(g0[0], u0[0]), silu_mul(g0[1], u0[1])); w.y = cvt_pk_bf16(silu_mul(g0[2], u0[2]), silu_mul(g0[3], u0[3]));
;                 w.z = cvt_pk_bf16(silu_mul(g1[0], u1[0]), silu_mul(g1[1], u1[1])); w.w = cvt_pk_bf16(silu_mul(g1[2], u1[2]), silu_mul(g1[3], u1[3]));
;                 *(u32x4*)(act + (((size_t)u.pm * (DFF / 64) + (u.pn * 2 + (wc >> 1))) * 256 + (row - u.pm * BM)) * 64 + (wc & 1) * 32 + 8 * fq) = w;
	v_lshl_add_u64 v[100:101], v[100:101], 0, v[200:201]
	global_store_dwordx4 v[100:101], v[96:99], off
	s_nop 1
	v_fmamk_f32 v96, v154, 0x3a000000, v143
	v_rsq_f32_e32 v96, v96
	s_nop 0
	v_pk_mul_f32 v[92:93], v[92:93], v[96:97] op_sel_hi:[1,0]
	v_pk_mul_f32 v[94:95], v[94:95], v[96:97] op_sel_hi:[1,0]
	v_pk_mul_f32 v[90:91], v[90:91], v[96:97] op_sel_hi:[1,0]
	v_pk_mul_f32 v[88:89], v[88:89], v[96:97] op_sel_hi:[1,0]
	v_pk_mul_f32 v[86:87], v[86:87], v[96:97] op_sel_hi:[1,0]
	v_pk_mul_f32 v[84:85], v[84:85], v[96:97] op_sel_hi:[1,0]
	v_pk_mul_f32 v[98:99], v[82:83], v[96:97] op_sel_hi:[1,0]
	v_pk_mul_f32 v[82:83], v[80:81], v[96:97] op_sel_hi:[1,0]
	v_pk_mul_f32 v[156:157], v[92:93], s[100:101]
	v_pk_mul_f32 v[158:159], v[94:95], s[100:101]
	v_exp_f32_e32 v156, v156
	v_exp_f32_e32 v157, v157
	v_exp_f32_e32 v158, v158
	v_exp_f32_e32 v159, v159
	v_pk_add_f32 v[156:157], v[156:157], 1.0 op_sel_hi:[1,0]
	v_pk_add_f32 v[158:159], v[158:159], 1.0 op_sel_hi:[1,0]
	v_rcp_f32_e32 v156, v156
	v_rcp_f32_e32 v157, v157
	v_rcp_f32_e32 v158, v158
	v_rcp_f32_e32 v159, v159
	v_pk_mul_f32 v[156:157], v[92:93], v[156:157]
	v_pk_mul_f32 v[158:159], v[94:95], v[158:159]
	v_pk_mul_f32 v[156:157], v[84:85], v[156:157]
	v_pk_mul_f32 v[158:159], v[86:87], v[158:159]
	v_pk_mul_f32 v[160:161], v[88:89], s[100:101]
	v_pk_mul_f32 v[162:163], v[90:91], s[100:101]
	v_exp_f32_e32 v160, v160
	v_exp_f32_e32 v161, v161
	v_exp_f32_e32 v162, v162
	v_exp_f32_e32 v163, v163
	v_pk_add_f32 v[160:161], v[160:161], 1.0 op_sel_hi:[1,0]
	v_pk_add_f32 v[162:163], v[162:163], 1.0 op_sel_hi:[1,0]
	v_rcp_f32_e32 v160, v160
	v_rcp_f32_e32 v161, v161
	v_rcp_f32_e32 v162, v162
	v_rcp_f32_e32 v163, v163
	v_pk_mul_f32 v[160:161], v[88:89], v[160:161]
	v_pk_mul_f32 v[162:163], v[90:91], v[162:163]
	v_pk_mul_f32 v[160:161], v[82:83], v[160:161]
	v_pk_mul_f32 v[162:163], v[98:99], v[162:163]
	v_cvt_pk_bf16_f32 v80, v156, v157
	v_cvt_pk_bf16_f32 v81, v158, v159
	v_cvt_pk_bf16_f32 v82, v160, v161
	v_cvt_pk_bf16_f32 v83, v162, v163
	v_subrev_u32_e32 v84, s21, v138
	v_ashrrev_i32_e32 v85, 31, v84
	v_lshlrev_b64 v[84:85], 7, v[84:85]
	v_lshl_add_u64 v[84:85], s[30:31], 0, v[84:85]
	v_lshl_add_u64 v[84:85], v[84:85], 0, s[16:17]
	v_lshl_add_u64 v[84:85], v[84:85], 0, v[200:201]
	global_store_dwordx4 v[84:85], v[80:83], off
	s_nop 1
	v_fmamk_f32 v80, v152, 0x3a000000, v143
	v_rsq_f32_e32 v80, v80
	s_nop 0
	v_pk_mul_f32 v[76:77], v[76:77], v[80:81] op_sel_hi:[1,0]
	v_pk_mul_f32 v[78:79], v[78:79], v[80:81] op_sel_hi:[1,0]
	v_pk_mul_f32 v[74:75], v[74:75], v[80:81] op_sel_hi:[1,0]
	v_pk_mul_f32 v[72:73], v[72:73], v[80:81] op_sel_hi:[1,0]
	v_pk_mul_f32 v[70:71], v[70:71], v[80:81] op_sel_hi:[1,0]
	v_pk_mul_f32 v[68:69], v[68:69], v[80:81] op_sel_hi:[1,0]
	v_pk_mul_f32 v[82:83], v[66:67], v[80:81] op_sel_hi:[1,0]
	v_pk_mul_f32 v[66:67], v[64:65], v[80:81] op_sel_hi:[1,0]
	v_pk_mul_f32 v[156:157], v[76:77], s[100:101]
	v_pk_mul_f32 v[158:159], v[78:79], s[100:101]
	v_exp_f32_e32 v156, v156
	v_exp_f32_e32 v157, v157
	v_exp_f32_e32 v158, v158
	v_exp_f32_e32 v159, v159
	v_pk_add_f32 v[156:157], v[156:157], 1.0 op_sel_hi:[1,0]
	v_pk_add_f32 v[158:159], v[158:159], 1.0 op_sel_hi:[1,0]
	v_rcp_f32_e32 v156, v156
	v_rcp_f32_e32 v157, v157
	v_rcp_f32_e32 v158, v158
	v_rcp_f32_e32 v159, v159
	v_pk_mul_f32 v[156:157], v[76:77], v[156:157]
	v_pk_mul_f32 v[158:159], v[78:79], v[158:159]
	v_pk_mul_f32 v[156:157], v[68:69], v[156:157]
	v_pk_mul_f32 v[158:159], v[70:71], v[158:159]
	v_pk_mul_f32 v[160:161], v[72:73], s[100:101]
	v_pk_mul_f32 v[162:163], v[74:75], s[100:101]
	v_exp_f32_e32 v160, v160
	v_exp_f32_e32 v161, v161
	v_exp_f32_e32 v162, v162
	v_exp_f32_e32 v163, v163
	v_pk_add_f32 v[160:161], v[160:161], 1.0 op_sel_hi:[1,0]
	v_pk_add_f32 v[162:163], v[162:163], 1.0 op_sel_hi:[1,0]
	v_rcp_f32_e32 v160, v160
	v_rcp_f32_e32 v161, v161
	v_rcp_f32_e32 v162, v162
	v_rcp_f32_e32 v163, v163
	v_pk_mul_f32 v[160:161], v[72:73], v[160:161]
	v_pk_mul_f32 v[162:163], v[74:75], v[162:163]
	v_pk_mul_f32 v[160:161], v[66:67], v[160:161]
	v_pk_mul_f32 v[162:163], v[82:83], v[162:163]
	v_cvt_pk_bf16_f32 v64, v156, v157
	v_cvt_pk_bf16_f32 v65, v158, v159
	v_cvt_pk_bf16_f32 v66, v160, v161
	v_cvt_pk_bf16_f32 v67, v162, v163
	v_subrev_u32_e32 v68, s21, v136
	v_ashrrev_i32_e32 v69, 31, v68
	v_lshlrev_b64 v[68:69], 7, v[68:69]
	v_lshl_add_u64 v[68:69], s[30:31], 0, v[68:69]
	v_lshl_add_u64 v[68:69], v[68:69], 0, s[16:17]
	v_lshl_add_u64 v[68:69], v[68:69], 0, v[200:201]
	global_store_dwordx4 v[68:69], v[64:67], off
	s_nop 1
	v_fmamk_f32 v64, v153, 0x3a000000, v143
	v_rsq_f32_e32 v64, v64
	s_nop 0
	v_pk_mul_f32 v[60:61], v[60:61], v[64:65] op_sel_hi:[1,0]
	v_pk_mul_f32 v[62:63], v[62:63], v[64:65] op_sel_hi:[1,0]
	v_pk_mul_f32 v[58:59], v[58:59], v[64:65] op_sel_hi:[1,0]
	v_pk_mul_f32 v[56:57], v[56:57], v[64:65] op_sel_hi:[1,0]
	v_pk_mul_f32 v[54:55], v[54:55], v[64:65] op_sel_hi:[1,0]
	v_pk_mul_f32 v[52:53], v[52:53], v[64:65] op_sel_hi:[1,0]
	v_pk_mul_f32 v[66:67], v[50:51], v[64:65] op_sel_hi:[1,0]
	v_pk_mul_f32 v[50:51], v[48:49], v[64:65] op_sel_hi:[1,0]
	v_pk_mul_f32 v[156:157], v[60:61], s[100:101]
	v_pk_mul_f32 v[158:159], v[62:63], s[100:101]
	v_exp_f32_e32 v156, v156
	v_exp_f32_e32 v157, v157
	v_exp_f32_e32 v158, v158
	v_exp_f32_e32 v159, v159
	v_pk_add_f32 v[156:157], v[156:157], 1.0 op_sel_hi:[1,0]
	v_pk_add_f32 v[158:159], v[158:159], 1.0 op_sel_hi:[1,0]
	v_rcp_f32_e32 v156, v156
	v_rcp_f32_e32 v157, v157
	v_rcp_f32_e32 v158, v158
	v_rcp_f32_e32 v159, v159
	v_pk_mul_f32 v[156:157], v[60:61], v[156:157]
	v_pk_mul_f32 v[158:159], v[62:63], v[158:159]
	v_pk_mul_f32 v[156:157], v[52:53], v[156:157]
; __device__ __forceinline__ unsigned cvt_pk_bf16(float lo, float hi) { unsigned r; asm volatile("v_cvt_pk_bf16_f32 %0, %1, %2" : "=v"(r) : "v"(lo), "v"(hi)); return r; }
; __device__ __forceinline__ float silu_mul(float g, float u) { return g * __builtin_amdgcn_rcpf(1.0f + __builtin_amdgcn_exp2f(-1.4426950408889634f * g)) * u; }
;     __device__ __forceinline__ void operator()(const f32x4 (&acc)[2][2][4][2], const Unit& u, int wr, int wc, int fr, int fq) const {
;     ...
;             for (int m = 0; m < 4; ++m) {
;                 const int row = row0 + ai * HALF + m * 16;
;                 const float r = __builtin_amdgcn_rsqf(rs[ai][m] * (1.0f / DM) + EPSN);
;                 const f32x4 g0 = acc[ai][0][m][0] * r, g1 = acc[ai][0][m][1] * r, u0 = acc[ai][1][m][0] * r, u1 = acc[ai][1][m][1] * r;
;                 u32x4 w;
;                 w.x = cvt_pk_bf16(silu_mul(g0[0], u0[0]), silu_mul(g0[1], u0[1])); w.y = cvt_pk_bf16(silu_mul(g0[2], u0[2]), silu_mul(g0[3], u0[3]));
;                 w.z = cvt_pk_bf16(silu_mul(g1[0], u1[0]), silu_mul(g1[1], u1[1])); w.w = cvt_pk_bf16(silu_mul(g1[2], u1[2]), silu_mul(g1[3], u1[3]));
;                 *(u32x4*)(act + (((size_t)u.pm * (DFF / 64) + (u.pn * 2 + (wc >> 1))) * 256 + (row - u.pm * BM)) * 64 + (wc & 1) * 32 + 8 * fq) = w;
	v_pk_mul_f32 v[158:159], v[54:55], v[158:159]
	v_pk_mul_f32 v[160:161], v[56:57], s[100:101]
	v_pk_mul_f32 v[162:163], v[58:59], s[100:101]
	v_exp_f32_e32 v160, v160
	v_exp_f32_e32 v161, v161
	v_exp_f32_e32 v162, v162
	v_exp_f32_e32 v163, v163
	v_pk_add_f32 v[160:161], v[160:161], 1.0 op_sel_hi:[1,0]
	v_pk_add_f32 v[162:163], v[162:163], 1.0 op_sel_hi:[1,0]
	v_rcp_f32_e32 v160, v160
	v_rcp_f32_e32 v161, v161
	v_rcp_f32_e32 v162, v162
	v_rcp_f32_e32 v163, v163
	v_pk_mul_f32 v[160:161], v[56:57], v[160:161]
	v_pk_mul_f32 v[162:163], v[58:59], v[162:163]
	v_pk_mul_f32 v[160:161], v[50:51], v[160:161]
	v_pk_mul_f32 v[162:163], v[66:67], v[162:163]
	v_cvt_pk_bf16_f32 v48, v156, v157
	v_cvt_pk_bf16_f32 v49, v158, v159
	v_cvt_pk_bf16_f32 v50, v160, v161
	v_cvt_pk_bf16_f32 v51, v162, v163
	v_add_u32_e32 v52, 0x80, v128
	v_mov_b32_e32 v53, v201
	v_lshlrev_b64 v[52:53], 7, v[52:53]
	v_lshl_add_u64 v[52:53], s[30:31], 0, v[52:53]
	v_lshl_add_u64 v[52:53], v[52:53], 0, s[16:17]
	v_lshl_add_u64 v[52:53], v[52:53], 0, v[200:201]
	global_store_dwordx4 v[52:53], v[48:51], off
	s_nop 1
	v_fmamk_f32 v48, v144, 0x3a000000, v143
	v_rsq_f32_e32 v48, v48
	s_nop 0
	v_pk_mul_f32 v[44:45], v[44:45], v[48:49] op_sel_hi:[1,0]
	v_pk_mul_f32 v[46:47], v[46:47], v[48:49] op_sel_hi:[1,0]
	v_pk_mul_f32 v[42:43], v[42:43], v[48:49] op_sel_hi:[1,0]
	v_pk_mul_f32 v[40:41], v[40:41], v[48:49] op_sel_hi:[1,0]
	v_pk_mul_f32 v[38:39], v[38:39], v[48:49] op_sel_hi:[1,0]
	v_pk_mul_f32 v[36:37], v[36:37], v[48:49] op_sel_hi:[1,0]
	v_pk_mul_f32 v[50:51], v[34:35], v[48:49] op_sel_hi:[1,0]
	v_pk_mul_f32 v[34:35], v[32:33], v[48:49] op_sel_hi:[1,0]
	v_pk_mul_f32 v[156:157], v[44:45], s[100:101]
	v_pk_mul_f32 v[158:159], v[46:47], s[100:101]
	v_exp_f32_e32 v156, v156
	v_exp_f32_e32 v157, v157
	v_exp_f32_e32 v158, v158
	v_exp_f32_e32 v159, v159
	v_pk_add_f32 v[156:157], v[156:157], 1.0 op_sel_hi:[1,0]
	v_pk_add_f32 v[158:159], v[158:159], 1.0 op_sel_hi:[1,0]
	v_rcp_f32_e32 v156, v156
	v_rcp_f32_e32 v157, v157
	v_rcp_f32_e32 v158, v158
	v_rcp_f32_e32 v159, v159
	v_pk_mul_f32 v[156:157], v[44:45], v[156:157]
	v_pk_mul_f32 v[158:159], v[46:47], v[158:159]
	v_pk_mul_f32 v[156:157], v[36:37], v[156:157]
	v_pk_mul_f32 v[158:159], v[38:39], v[158:159]
	v_pk_mul_f32 v[160:161], v[40:41], s[100:101]
	v_pk_mul_f32 v[162:163], v[42:43], s[100:101]
	v_exp_f32_e32 v160, v160
	v_exp_f32_e32 v161, v161
	v_exp_f32_e32 v162, v162
	v_exp_f32_e32 v163, v163
	v_pk_add_f32 v[160:161], v[160:161], 1.0 op_sel_hi:[1,0]
	v_pk_add_f32 v[162:163], v[162:163], 1.0 op_sel_hi:[1,0]
	v_rcp_f32_e32 v160, v160
	v_rcp_f32_e32 v161, v161
	v_rcp_f32_e32 v162, v162
	v_rcp_f32_e32 v163, v163
	v_pk_mul_f32 v[160:161], v[40:41], v[160:161]
	v_pk_mul_f32 v[162:163], v[42:43], v[162:163]
	v_pk_mul_f32 v[160:161], v[34:35], v[160:161]
	v_pk_mul_f32 v[162:163], v[50:51], v[162:163]
	v_cvt_pk_bf16_f32 v32, v156, v157
	v_cvt_pk_bf16_f32 v33, v158, v159
	v_cvt_pk_bf16_f32 v34, v160, v161
	v_cvt_pk_bf16_f32 v35, v162, v163
	v_add_u32_e32 v36, 0x90, v128
	v_mov_b32_e32 v37, v201
	v_lshlrev_b64 v[36:37], 7, v[36:37]
	v_lshl_add_u64 v[36:37], s[30:31], 0, v[36:37]
	v_lshl_add_u64 v[36:37], v[36:37], 0, s[16:17]
	v_lshl_add_u64 v[36:37], v[36:37], 0, v[200:201]
	global_store_dwordx4 v[36:37], v[32:35], off
	s_nop 1
	v_fmamk_f32 v32, v139, 0x3a000000, v143
	v_rsq_f32_e32 v32, v32
	s_nop 0
	v_pk_mul_f32 v[28:29], v[28:29], v[32:33] op_sel_hi:[1,0]
	v_pk_mul_f32 v[30:31], v[30:31], v[32:33] op_sel_hi:[1,0]
	v_pk_mul_f32 v[26:27], v[26:27], v[32:33] op_sel_hi:[1,0]
	v_pk_mul_f32 v[24:25], v[24:25], v[32:33] op_sel_hi:[1,0]
	v_pk_mul_f32 v[22:23], v[22:23], v[32:33] op_sel_hi:[1,0]
	v_pk_mul_f32 v[20:21], v[20:21], v[32:33] op_sel_hi:[1,0]
	v_pk_mul_f32 v[34:35], v[18:19], v[32:33] op_sel_hi:[1,0]
	v_pk_mul_f32 v[18:19], v[16:17], v[32:33] op_sel_hi:[1,0]
	v_pk_mul_f32 v[156:157], v[28:29], s[100:101]
; __device__ __forceinline__ unsigned cvt_pk_bf16(float lo, float hi) { unsigned r; asm volatile("v_cvt_pk_bf16_f32 %0, %1, %2" : "=v"(r) : "v"(lo), "v"(hi)); return r; }
; __device__ __forceinline__ float silu_mul(float g, float u) { return g * __builtin_amdgcn_rcpf(1.0f + __builtin_amdgcn_exp2f(-1.4426950408889634f * g)) * u; }
;     __device__ __forceinline__ void operator()(const f32x4 (&acc)[2][2][4][2], const Unit& u, int wr, int wc, int fr, int fq) const {
;     ...
;             for (int m = 0; m < 4; ++m) {
;                 const int row = row0 + ai * HALF + m * 16;
;                 const float r = __builtin_amdgcn_rsqf(rs[ai][m] * (1.0f / DM) + EPSN);
;                 const f32x4 g0 = acc[ai][0][m][0] * r, g1 = acc[ai][0][m][1] * r, u0 = acc[ai][1][m][0] * r, u1 = acc[ai][1][m][1] * r;
;                 u32x4 w;
;                 w.x = cvt_pk_bf16(silu_mul(g0[0], u0[0]), silu_mul(g0[1], u0[1])); w.y = cvt_pk_bf16(silu_mul(g0[2], u0[2]), silu_mul(g0[3], u0[3]));
;                 w.z = cvt_pk_bf16(silu_mul(g1[0], u1[0]), silu_mul(g1[1], u1[1])); w.w = cvt_pk_bf16(silu_mul(g1[2], u1[2]), silu_mul(g1[3], u1[3]));
;                 *(u32x4*)(act + (((size_t)u.pm * (DFF / 64) + (u.pn * 2 + (wc >> 1))) * 256 + (row - u.pm * BM)) * 64 + (wc & 1) * 32 + 8 * fq) = w;
	v_pk_mul_f32 v[158:159], v[30:31], s[100:101]
	v_exp_f32_e32 v156, v156
	v_exp_f32_e32 v157, v157
	v_exp_f32_e32 v158, v158
	v_exp_f32_e32 v159, v159
	v_pk_add_f32 v[156:157], v[156:157], 1.0 op_sel_hi:[1,0]
	v_pk_add_f32 v[158:159], v[158:159], 1.0 op_sel_hi:[1,0]
	v_rcp_f32_e32 v156, v156
	v_rcp_f32_e32 v157, v157
	v_rcp_f32_e32 v158, v158
	v_rcp_f32_e32 v159, v159
	v_pk_mul_f32 v[156:157], v[28:29], v[156:157]
	v_pk_mul_f32 v[158:159], v[30:31], v[158:159]
	v_pk_mul_f32 v[156:157], v[20:21], v[156:157]
	v_pk_mul_f32 v[158:159], v[22:23], v[158:159]
	v_pk_mul_f32 v[160:161], v[24:25], s[100:101]
	v_pk_mul_f32 v[162:163], v[26:27], s[100:101]
	v_exp_f32_e32 v160, v160
	v_exp_f32_e32 v161, v161
	v_exp_f32_e32 v162, v162
	v_exp_f32_e32 v163, v163
	v_pk_add_f32 v[160:161], v[160:161], 1.0 op_sel_hi:[1,0]
	v_pk_add_f32 v[162:163], v[162:163], 1.0 op_sel_hi:[1,0]
	v_rcp_f32_e32 v160, v160
	v_rcp_f32_e32 v161, v161
	v_rcp_f32_e32 v162, v162
	v_rcp_f32_e32 v163, v163
	v_pk_mul_f32 v[160:161], v[24:25], v[160:161]
	v_pk_mul_f32 v[162:163], v[26:27], v[162:163]
	v_pk_mul_f32 v[160:161], v[18:19], v[160:161]
	v_pk_mul_f32 v[162:163], v[34:35], v[162:163]
	v_cvt_pk_bf16_f32 v16, v156, v157
	v_cvt_pk_bf16_f32 v17, v158, v159
	v_cvt_pk_bf16_f32 v18, v160, v161
	v_cvt_pk_bf16_f32 v19, v162, v163
	v_add_u32_e32 v20, 0xa0, v128
	v_mov_b32_e32 v21, v201
	v_lshlrev_b64 v[20:21], 7, v[20:21]
	v_lshl_add_u64 v[20:21], s[30:31], 0, v[20:21]
	v_lshl_add_u64 v[20:21], v[20:21], 0, s[16:17]
	v_lshl_add_u64 v[20:21], v[20:21], 0, v[200:201]
	global_store_dwordx4 v[20:21], v[16:19], off
	s_nop 1
	v_fmamk_f32 v16, v137, 0x3a000000, v143
	v_rsq_f32_e32 v16, v16
	s_nop 0
	v_pk_mul_f32 v[12:13], v[12:13], v[16:17] op_sel_hi:[1,0]
	v_pk_mul_f32 v[14:15], v[14:15], v[16:17] op_sel_hi:[1,0]
	v_pk_mul_f32 v[10:11], v[10:11], v[16:17] op_sel_hi:[1,0]
	v_pk_mul_f32 v[8:9], v[8:9], v[16:17] op_sel_hi:[1,0]
	v_pk_mul_f32 v[6:7], v[6:7], v[16:17] op_sel_hi:[1,0]
	v_pk_mul_f32 v[4:5], v[4:5], v[16:17] op_sel_hi:[1,0]
	v_pk_mul_f32 v[18:19], v[2:3], v[16:17] op_sel_hi:[1,0]
	v_pk_mul_f32 v[2:3], v[0:1], v[16:17] op_sel_hi:[1,0]
	v_pk_mul_f32 v[156:157], v[12:13], s[100:101]
	v_pk_mul_f32 v[158:159], v[14:15], s[100:101]
	v_exp_f32_e32 v156, v156
	v_exp_f32_e32 v157, v157
	v_exp_f32_e32 v158, v158
	v_exp_f32_e32 v159, v159
	v_pk_add_f32 v[156:157], v[156:157], 1.0 op_sel_hi:[1,0]
	v_pk_add_f32 v[158:159], v[158:159], 1.0 op_sel_hi:[1,0]
	v_rcp_f32_e32 v156, v156
	v_rcp_f32_e32 v157, v157
	v_rcp_f32_e32 v158, v158
	v_rcp_f32_e32 v159, v159
	v_pk_mul_f32 v[156:157], v[12:13], v[156:157]
	v_pk_mul_f32 v[158:159], v[14:15], v[158:159]
	v_pk_mul_f32 v[156:157], v[4:5], v[156:157]
	v_pk_mul_f32 v[158:159], v[6:7], v[158:159]
	v_pk_mul_f32 v[160:161], v[8:9], s[100:101]
	v_pk_mul_f32 v[162:163], v[10:11], s[100:101]
	v_exp_f32_e32 v160, v160
	v_exp_f32_e32 v161, v161
	v_exp_f32_e32 v162, v162
	v_exp_f32_e32 v163, v163
	v_pk_add_f32 v[160:161], v[160:161], 1.0 op_sel_hi:[1,0]
	v_pk_add_f32 v[162:163], v[162:163], 1.0 op_sel_hi:[1,0]
	v_rcp_f32_e32 v160, v160
	v_rcp_f32_e32 v161, v161
	v_rcp_f32_e32 v162, v162
	v_rcp_f32_e32 v163, v163
	v_pk_mul_f32 v[160:161], v[8:9], v[160:161]
	v_pk_mul_f32 v[162:163], v[10:11], v[162:163]
	v_pk_mul_f32 v[160:161], v[2:3], v[160:161]
	v_pk_mul_f32 v[162:163], v[18:19], v[162:163]
	v_cvt_pk_bf16_f32 v0, v156, v157
	v_cvt_pk_bf16_f32 v1, v158, v159
	v_cvt_pk_bf16_f32 v2, v160, v161
	v_cvt_pk_bf16_f32 v3, v162, v163
	v_add_u32_e32 v4, 0xb0, v128
	v_mov_b32_e32 v5, v201
	v_lshlrev_b64 v[4:5], 7, v[4:5]
	v_lshl_add_u64 v[4:5], s[30:31], 0, v[4:5]
	v_lshl_add_u64 v[4:5], v[4:5], 0, s[16:17]
	v_lshl_add_u64 v[4:5], v[4:5], 0, v[200:201]
	global_store_dwordx4 v[4:5], v[0:3], off
	s_andn2_b64 vcc, exec, s[24:25]
	s_mov_b64 s[24:25], -1
	s_cbranch_vccnz .LBB0_1331
	s_andn2_b64 vcc, exec, s[0:1]
	s_cbranch_vccnz .LBB0_1330
	s_barrier
	s_branch .LBB0_1330
